# FFN GEMM loops: snake MFMA order (every consecutive MFMA pair shares src1 or the accumulator) + nt FFN-up stores
# baseline (speedup 1.0000x reference)
; #define PG8_STAGE(bufoff, gbase, voff) do { _Pragma("unroll") for (int _i = 0; _i < 2; ++_i) \
;         __builtin_amdgcn_global_load_lds((const unsigned*)((const char*)(gbase) + (size_t)_i * p##voff + (voff)), (LAS unsigned*)(lds + (bufoff) + ldsw + _i * 8192), 16, 0, 0); } while (0)
; #define PG8_LDA(dst, b, h) do { _Pragma("unroll") for (int m = 0; m < 4; ++m) _Pragma("unroll") for (int k = 0; k < 2; ++k) dst[m][k] = *(const LAS bf16x8*)(lds + PG8_SA(b, h) + aoff + m * 2048 + k * 1024); } while (0)
; #define PG8_LDB(dst, b, h) do { _Pragma("unroll") for (int n = 0; n < 2; ++n) _Pragma("unroll") for (int k = 0; k < 2; ++k) dst[n][k] = *(const LAS bf16x8*)(lds + PG8_SB(b, h) + boff + n * 2048 + k * 1024); } while (0)
; #define PG8_WAIT_V(n) asm volatile("s_waitcnt vmcnt(" #n ")" ::: "memory")
; #define PG8_WAIT_L(n) asm volatile("s_waitcnt lgkmcnt(" #n ")" ::: "memory")
; #define PG8_BAR __builtin_amdgcn_s_barrier()
; #define PG8_SCHED __builtin_amdgcn_sched_barrier(0)
;     ...
;             PG8_LDB(B0, 0, 0); PG8_LDB(B1, 0, 1); PG8_SCHED; PG8_LDA(At, 0, 0); PG8_STAGE(PG8_SA(1, 1), a1 + hstepA, voffA);
;             PG8_WAIT_V(8); PG8_WAIT_L(0); PG8_BAR; PG8_MMA(0, 0, At, B0); PG8_MMA(0, 1, At, B1); PG8_BAR; PG8_SCHED;
;             PG8_LDA(At, 0, 1); PG8_STAGE(PG8_SB(0, 0), b2, voffB); PG8_STAGE(PG8_SB(0, 1), b2 + hstepB, voffB); PG8_STAGE(PG8_SA(0, 0), a2, voffA);
;             PG8_WAIT_V(8); PG8_WAIT_L(0); PG8_BAR; PG8_MMA(1, 0, At, B0); PG8_MMA(1, 1, At, B1); PG8_BAR; PG8_SCHED;
.LBB0_1206:
	ds_read_b128 v[148:151], v144
	ds_read_b128 v[152:155], v144 offset:1024
	ds_read_b128 v[156:159], v144 offset:2048
	ds_read_b128 v[160:163], v144 offset:3072
	ds_read_b128 v[164:167], v145
	ds_read_b128 v[168:171], v145 offset:1024
	ds_read_b128 v[172:175], v145 offset:2048
	ds_read_b128 v[176:179], v145 offset:3072
	s_add_u32 s46, s42, s44
	s_addc_u32 s47, s43, s45
	s_add_u32 s74, s46, 0x10000
	s_addc_u32 s75, s47, 0
	s_add_u32 s46, s46, 0x18000
	s_addc_u32 s47, s47, 0
	s_cmp_eq_u32 s44, 0x1f0000
	s_cselect_b32 s47, s68, s47
	s_cselect_b32 s46, s67, s46
	s_cselect_b32 s73, s29, s70
	s_cselect_b32 s72, s66, s69
	s_cselect_b32 s75, s35, s75
	s_cselect_b32 s74, s65, s74
	v_lshl_add_u64 v[184:185], v[142:143], 0, s[44:45]
	v_lshl_add_u64 v[216:217], v[184:185], 0, s[76:77]
	s_add_i32 m0, s52, 0xc000
	ds_read_b128 v[180:183], v146
	ds_read_b128 v[188:191], v146 offset:1024
	ds_read_b128 v[192:195], v146 offset:2048
	ds_read_b128 v[196:199], v146 offset:3072
	ds_read_b128 v[200:203], v146 offset:4096
	ds_read_b128 v[204:207], v146 offset:5120
	ds_read_b128 v[208:211], v146 offset:6144
	ds_read_b128 v[212:215], v146 offset:7168
	global_load_lds_dwordx4 v[216:217], off
	v_lshl_add_u64 v[184:185], v[184:185], 0, s[26:27]
	s_add_i32 m0, s52, 0xe000
	s_nop 0
	global_load_lds_dwordx4 v[184:185], off
	s_waitcnt vmcnt(8)
	s_waitcnt lgkmcnt(0)
	s_barrier
	s_setprio 1
	s_waitcnt lgkmcnt(0)
	v_mfma_f32_16x16x32_bf16 v[126:129], v[148:151], v[180:183], v[126:129]
	v_mfma_f32_16x16x32_bf16 v[122:125], v[156:159], v[180:183], v[122:125]
	v_mfma_f32_16x16x32_bf16 v[122:125], v[160:163], v[188:191], v[122:125]
	v_mfma_f32_16x16x32_bf16 v[126:129], v[152:155], v[188:191], v[126:129]
	v_mfma_f32_16x16x32_bf16 v[110:113], v[148:151], v[192:195], v[110:113]
	v_mfma_f32_16x16x32_bf16 v[106:109], v[156:159], v[192:195], v[106:109]
	v_mfma_f32_16x16x32_bf16 v[106:109], v[160:163], v[196:199], v[106:109]
	v_mfma_f32_16x16x32_bf16 v[110:113], v[152:155], v[196:199], v[110:113]
	v_mfma_f32_16x16x32_bf16 v[94:97], v[148:151], v[200:203], v[94:97]
	v_mfma_f32_16x16x32_bf16 v[90:93], v[156:159], v[200:203], v[90:93]
	v_mfma_f32_16x16x32_bf16 v[90:93], v[160:163], v[204:207], v[90:93]
	v_mfma_f32_16x16x32_bf16 v[94:97], v[152:155], v[204:207], v[94:97]
	v_mfma_f32_16x16x32_bf16 v[78:81], v[148:151], v[208:211], v[78:81]
	v_mfma_f32_16x16x32_bf16 v[74:77], v[156:159], v[208:211], v[74:77]
	v_mfma_f32_16x16x32_bf16 v[74:77], v[160:163], v[212:215], v[74:77]
	v_mfma_f32_16x16x32_bf16 v[78:81], v[152:155], v[212:215], v[78:81]
	s_setprio 0
	s_setprio 1
	v_mfma_f32_16x16x32_bf16 v[118:121], v[164:167], v[180:183], v[118:121]
	v_mfma_f32_16x16x32_bf16 v[114:117], v[172:175], v[180:183], v[114:117]
	v_mfma_f32_16x16x32_bf16 v[114:117], v[176:179], v[188:191], v[114:117]
	v_mfma_f32_16x16x32_bf16 v[118:121], v[168:171], v[188:191], v[118:121]
	v_mfma_f32_16x16x32_bf16 v[102:105], v[164:167], v[192:195], v[102:105]
	v_mfma_f32_16x16x32_bf16 v[98:101], v[172:175], v[192:195], v[98:101]
	v_mfma_f32_16x16x32_bf16 v[98:101], v[176:179], v[196:199], v[98:101]
	v_mfma_f32_16x16x32_bf16 v[102:105], v[168:171], v[196:199], v[102:105]
	v_mfma_f32_16x16x32_bf16 v[86:89], v[164:167], v[200:203], v[86:89]
	v_mfma_f32_16x16x32_bf16 v[82:85], v[172:175], v[200:203], v[82:85]
	v_mfma_f32_16x16x32_bf16 v[82:85], v[176:179], v[204:207], v[82:85]
	v_mfma_f32_16x16x32_bf16 v[86:89], v[168:171], v[204:207], v[86:89]
	v_mfma_f32_16x16x32_bf16 v[70:73], v[164:167], v[208:211], v[70:73]
	v_mfma_f32_16x16x32_bf16 v[66:69], v[172:175], v[208:211], v[66:69]
	v_mfma_f32_16x16x32_bf16 v[66:69], v[176:179], v[212:215], v[66:69]
	v_mfma_f32_16x16x32_bf16 v[70:73], v[168:171], v[212:215], v[70:73]
	s_setprio 0
	s_barrier
	v_lshl_add_u64 v[184:185], s[72:73], 0, v[132:133]
	s_add_i32 s72, s63, s50
	s_mov_b32 m0, s72
	ds_read_b128 v[180:183], v146 offset:16384
	ds_read_b128 v[188:191], v146 offset:17408
	ds_read_b128 v[192:195], v146 offset:18432
	ds_read_b128 v[196:199], v146 offset:19456
	ds_read_b128 v[200:203], v146 offset:20480
	ds_read_b128 v[204:207], v146 offset:21504
	ds_read_b128 v[208:211], v146 offset:22528
	ds_read_b128 v[212:215], v146 offset:23552
	global_load_lds_dwordx4 v[184:185], off
	v_lshl_add_u64 v[216:217], v[184:185], 0, s[4:5]
	s_add_i32 m0, s72, 0x2000
	s_add_i32 s72, s64, s50
	global_load_lds_dwordx4 v[216:217], off
	v_lshl_add_u64 v[216:217], v[184:185], 0, s[6:7]
	s_mov_b32 m0, s72
	s_nop 0
	global_load_lds_dwordx4 v[216:217], off
	v_lshl_add_u64 v[216:217], v[184:185], 0, s[8:9]
	s_add_i32 m0, s72, 0x2000
	s_nop 0
	global_load_lds_dwordx4 v[216:217], off
	v_lshl_add_u64 v[216:217], s[74:75], 0, v[130:131]
	s_mov_b32 m0, s52
	v_lshl_add_u64 v[218:219], v[216:217], 0, s[10:11]
	global_load_lds_dwordx4 v[216:217], off
	s_mov_b32 m0, s53
	s_nop 0
	global_load_lds_dwordx4 v[218:219], off
	s_waitcnt vmcnt(8)
	s_waitcnt lgkmcnt(0)
	s_barrier
; #define PG8_STAGE(bufoff, gbase, voff) do { _Pragma("unroll") for (int _i = 0; _i < 2; ++_i) \
;         __builtin_amdgcn_global_load_lds((const unsigned*)((const char*)(gbase) + (size_t)_i * p##voff + (voff)), (LAS unsigned*)(lds + (bufoff) + ldsw + _i * 8192), 16, 0, 0); } while (0)
; #define PG8_LDA(dst, b, h) do { _Pragma("unroll") for (int m = 0; m < 4; ++m) _Pragma("unroll") for (int k = 0; k < 2; ++k) dst[m][k] = *(const LAS bf16x8*)(lds + PG8_SA(b, h) + aoff + m * 2048 + k * 1024); } while (0)
; #define PG8_LDB(dst, b, h) do { _Pragma("unroll") for (int n = 0; n < 2; ++n) _Pragma("unroll") for (int k = 0; k < 2; ++k) dst[n][k] = *(const LAS bf16x8*)(lds + PG8_SB(b, h) + boff + n * 2048 + k * 1024); } while (0)
; #define PG8_WAIT_V(n) asm volatile("s_waitcnt vmcnt(" #n ")" ::: "memory")
; #define PG8_WAIT_L(n) asm volatile("s_waitcnt lgkmcnt(" #n ")" ::: "memory")
; #define PG8_BAR __builtin_amdgcn_s_barrier()
; #define PG8_SCHED __builtin_amdgcn_sched_barrier(0)
;     ...
;             PG8_LDB(B0, 0, 0); PG8_LDB(B1, 0, 1); PG8_SCHED; PG8_LDA(At, 0, 0); PG8_STAGE(PG8_SA(1, 1), a1 + hstepA, voffA);
;             PG8_WAIT_V(8); PG8_WAIT_L(0); PG8_BAR; PG8_MMA(0, 0, At, B0); PG8_MMA(0, 1, At, B1); PG8_BAR; PG8_SCHED;
;             PG8_LDA(At, 0, 1); PG8_STAGE(PG8_SB(0, 0), b2, voffB); PG8_STAGE(PG8_SB(0, 1), b2 + hstepB, voffB); PG8_STAGE(PG8_SA(0, 0), a2, voffA);
;             PG8_WAIT_V(8); PG8_WAIT_L(0); PG8_BAR; PG8_MMA(1, 0, At, B0); PG8_MMA(1, 1, At, B1); PG8_BAR; PG8_SCHED;
;             PG8_LDB(B0, 1, 0); PG8_LDB(B1, 1, 1); PG8_SCHED; PG8_LDA(At, 1, 0); PG8_STAGE(PG8_SA(0, 1), a2 + hstepA, voffA);
;             PG8_WAIT_V(8); PG8_WAIT_L(0); PG8_BAR; PG8_MMA(0, 0, At, B0); PG8_MMA(0, 1, At, B1); PG8_BAR; PG8_SCHED;
	s_setprio 1
	s_waitcnt lgkmcnt(0)
	v_mfma_f32_16x16x32_bf16 v[62:65], v[148:151], v[180:183], v[62:65]
	v_mfma_f32_16x16x32_bf16 v[58:61], v[156:159], v[180:183], v[58:61]
	v_mfma_f32_16x16x32_bf16 v[58:61], v[160:163], v[188:191], v[58:61]
	v_mfma_f32_16x16x32_bf16 v[62:65], v[152:155], v[188:191], v[62:65]
	v_mfma_f32_16x16x32_bf16 v[46:49], v[148:151], v[192:195], v[46:49]
	v_mfma_f32_16x16x32_bf16 v[42:45], v[156:159], v[192:195], v[42:45]
	v_mfma_f32_16x16x32_bf16 v[42:45], v[160:163], v[196:199], v[42:45]
	v_mfma_f32_16x16x32_bf16 v[46:49], v[152:155], v[196:199], v[46:49]
	v_mfma_f32_16x16x32_bf16 v[30:33], v[148:151], v[200:203], v[30:33]
	v_mfma_f32_16x16x32_bf16 v[26:29], v[156:159], v[200:203], v[26:29]
	v_mfma_f32_16x16x32_bf16 v[26:29], v[160:163], v[204:207], v[26:29]
	v_mfma_f32_16x16x32_bf16 v[30:33], v[152:155], v[204:207], v[30:33]
	v_mfma_f32_16x16x32_bf16 v[14:17], v[148:151], v[208:211], v[14:17]
	v_mfma_f32_16x16x32_bf16 v[10:13], v[156:159], v[208:211], v[10:13]
	v_mfma_f32_16x16x32_bf16 v[10:13], v[160:163], v[212:215], v[10:13]
	v_mfma_f32_16x16x32_bf16 v[14:17], v[152:155], v[212:215], v[14:17]
	s_setprio 0
	s_setprio 1
	v_mfma_f32_16x16x32_bf16 v[54:57], v[164:167], v[180:183], v[54:57]
	v_mfma_f32_16x16x32_bf16 v[50:53], v[172:175], v[180:183], v[50:53]
	v_mfma_f32_16x16x32_bf16 v[50:53], v[176:179], v[188:191], v[50:53]
	v_mfma_f32_16x16x32_bf16 v[54:57], v[168:171], v[188:191], v[54:57]
	v_mfma_f32_16x16x32_bf16 v[38:41], v[164:167], v[192:195], v[38:41]
	v_mfma_f32_16x16x32_bf16 v[34:37], v[172:175], v[192:195], v[34:37]
	v_mfma_f32_16x16x32_bf16 v[34:37], v[176:179], v[196:199], v[34:37]
	v_mfma_f32_16x16x32_bf16 v[38:41], v[168:171], v[196:199], v[38:41]
	v_mfma_f32_16x16x32_bf16 v[22:25], v[164:167], v[200:203], v[22:25]
	v_mfma_f32_16x16x32_bf16 v[18:21], v[172:175], v[200:203], v[18:21]
	v_mfma_f32_16x16x32_bf16 v[18:21], v[176:179], v[204:207], v[18:21]
	v_mfma_f32_16x16x32_bf16 v[22:25], v[168:171], v[204:207], v[22:25]
	v_mfma_f32_16x16x32_bf16 v[6:9], v[164:167], v[208:211], v[6:9]
	v_mfma_f32_16x16x32_bf16 v[2:5], v[172:175], v[208:211], v[2:5]
	v_mfma_f32_16x16x32_bf16 v[2:5], v[176:179], v[212:215], v[2:5]
	v_mfma_f32_16x16x32_bf16 v[6:9], v[168:171], v[212:215], v[6:9]
	s_setprio 0
	s_barrier
	s_add_i32 s72, 0, 0x18000
	s_add_i32 s73, 0, 0x1c000
	v_add_u32_e32 v160, s72, v1
	v_add_u32_e32 v176, s73, v1
	ds_read_b128 v[148:151], v160
	ds_read_b128 v[152:155], v160 offset:1024
	ds_read_b128 v[156:159], v160 offset:2048
	ds_read_b128 v[160:163], v160 offset:3072
	ds_read_b128 v[164:167], v176
	ds_read_b128 v[168:171], v176 offset:1024
	ds_read_b128 v[172:175], v176 offset:2048
	ds_read_b128 v[176:179], v176 offset:3072
	s_mov_b32 m0, s54
	v_lshl_add_u64 v[218:219], v[216:217], 0, s[12:13]
	ds_read_b128 v[180:183], v146 offset:32768
	ds_read_b128 v[188:191], v146 offset:33792
	ds_read_b128 v[192:195], v146 offset:34816
	ds_read_b128 v[196:199], v146 offset:35840
	ds_read_b128 v[200:203], v146 offset:36864
	ds_read_b128 v[204:207], v146 offset:37888
	ds_read_b128 v[208:211], v146 offset:38912
	ds_read_b128 v[212:215], v146 offset:39936
	global_load_lds_dwordx4 v[218:219], off
	v_lshl_add_u64 v[216:217], v[216:217], 0, s[14:15]
	s_mov_b32 m0, s55
	s_nop 0
	global_load_lds_dwordx4 v[216:217], off
	s_waitcnt vmcnt(8)
	s_waitcnt lgkmcnt(0)
	s_barrier
	s_setprio 1
	s_waitcnt lgkmcnt(0)
	v_mfma_f32_16x16x32_bf16 v[126:129], v[148:151], v[180:183], v[126:129]
	v_mfma_f32_16x16x32_bf16 v[122:125], v[156:159], v[180:183], v[122:125]
	v_mfma_f32_16x16x32_bf16 v[122:125], v[160:163], v[188:191], v[122:125]
	v_mfma_f32_16x16x32_bf16 v[126:129], v[152:155], v[188:191], v[126:129]
	v_mfma_f32_16x16x32_bf16 v[110:113], v[148:151], v[192:195], v[110:113]
	v_mfma_f32_16x16x32_bf16 v[106:109], v[156:159], v[192:195], v[106:109]
	v_mfma_f32_16x16x32_bf16 v[106:109], v[160:163], v[196:199], v[106:109]
	v_mfma_f32_16x16x32_bf16 v[110:113], v[152:155], v[196:199], v[110:113]
	v_mfma_f32_16x16x32_bf16 v[94:97], v[148:151], v[200:203], v[94:97]
	v_mfma_f32_16x16x32_bf16 v[90:93], v[156:159], v[200:203], v[90:93]
	v_mfma_f32_16x16x32_bf16 v[90:93], v[160:163], v[204:207], v[90:93]
	v_mfma_f32_16x16x32_bf16 v[94:97], v[152:155], v[204:207], v[94:97]
	v_mfma_f32_16x16x32_bf16 v[78:81], v[148:151], v[208:211], v[78:81]
	v_mfma_f32_16x16x32_bf16 v[74:77], v[156:159], v[208:211], v[74:77]
	v_mfma_f32_16x16x32_bf16 v[74:77], v[160:163], v[212:215], v[74:77]
	v_mfma_f32_16x16x32_bf16 v[78:81], v[152:155], v[212:215], v[78:81]
	s_setprio 0
	s_setprio 1
	v_mfma_f32_16x16x32_bf16 v[118:121], v[164:167], v[180:183], v[118:121]
	v_mfma_f32_16x16x32_bf16 v[114:117], v[172:175], v[180:183], v[114:117]
	v_mfma_f32_16x16x32_bf16 v[114:117], v[176:179], v[188:191], v[114:117]
	v_mfma_f32_16x16x32_bf16 v[118:121], v[168:171], v[188:191], v[118:121]
	v_mfma_f32_16x16x32_bf16 v[102:105], v[164:167], v[192:195], v[102:105]
	v_mfma_f32_16x16x32_bf16 v[98:101], v[172:175], v[192:195], v[98:101]
	v_mfma_f32_16x16x32_bf16 v[98:101], v[176:179], v[196:199], v[98:101]
	v_mfma_f32_16x16x32_bf16 v[102:105], v[168:171], v[196:199], v[102:105]
	v_mfma_f32_16x16x32_bf16 v[86:89], v[164:167], v[200:203], v[86:89]
	v_mfma_f32_16x16x32_bf16 v[82:85], v[172:175], v[200:203], v[82:85]
	v_mfma_f32_16x16x32_bf16 v[82:85], v[176:179], v[204:207], v[82:85]
	v_mfma_f32_16x16x32_bf16 v[86:89], v[168:171], v[204:207], v[86:89]
	v_mfma_f32_16x16x32_bf16 v[70:73], v[164:167], v[208:211], v[70:73]
	v_mfma_f32_16x16x32_bf16 v[66:69], v[172:175], v[208:211], v[66:69]
	v_mfma_f32_16x16x32_bf16 v[66:69], v[176:179], v[212:215], v[66:69]
	v_mfma_f32_16x16x32_bf16 v[70:73], v[168:171], v[212:215], v[70:73]
	s_setprio 0
	s_barrier
; __device__ __forceinline__ unsigned cvtpk(float lo, float hi) { f32x2 v = {lo, hi}; bf16x2_t b = __builtin_convertvector(v, bf16x2_t); return __builtin_bit_cast(unsigned, b); }
; #define PG8_STAGE(bufoff, gbase, voff) do { _Pragma("unroll") for (int _i = 0; _i < 2; ++_i) \
;         __builtin_amdgcn_global_load_lds((const unsigned*)((const char*)(gbase) + (size_t)_i * p##voff + (voff)), (LAS unsigned*)(lds + (bufoff) + ldsw + _i * 8192), 16, 0, 0); } while (0)
; #define PG8_LDA(dst, b, h) do { _Pragma("unroll") for (int m = 0; m < 4; ++m) _Pragma("unroll") for (int k = 0; k < 2; ++k) dst[m][k] = *(const LAS bf16x8*)(lds + PG8_SA(b, h) + aoff + m * 2048 + k * 1024); } while (0)
; #define PG8_WAIT_V(n) asm volatile("s_waitcnt vmcnt(" #n ")" ::: "memory")
; #define PG8_WAIT_L(n) asm volatile("s_waitcnt lgkmcnt(" #n ")" ::: "memory")
; #define PG8_BAR __builtin_amdgcn_s_barrier()
; #define PG8_SCHED __builtin_amdgcn_sched_barrier(0)
;     ...
;             PG8_LDA(At, 1, 1); PG8_STAGE(PG8_SB(1, 0), b3, voffB); PG8_STAGE(PG8_SB(1, 1), b3 + hstepB, voffB); PG8_STAGE(PG8_SA(1, 0), a3, voffA);
;             PG8_WAIT_V(8); PG8_WAIT_L(0); PG8_BAR; PG8_MMA(1, 0, At, B0); PG8_MMA(1, 1, At, B1); PG8_BAR; PG8_SCHED;
;     __device__ __forceinline__ void operator()(const Acc& acc, const Unit& u, int wr, int wc, int fr, int fq) const {
;     ...
;         const int rl = wr * 64 + fr, kt0 = u.pn * 4 + (wc >> 1), cl = (wc & 1) * 32 + 8 * fq;
; #pragma unroll
;         for (int ai = 0; ai < 2; ++ai)
; #pragma unroll
;             for (int m = 0; m < 4; ++m) { bf16_t* rp = O + (((size_t)u.pm * (DFF / 64) + kt0) * 256 + (rl + ai * 128 + m * 16)) * 64 + cl;
; #pragma unroll
;                 for (int bj = 0; bj < 2; ++bj) { f32x4 v0 = acc[ai][bj][m][0], v1 = acc[ai][bj][m][1];
; #pragma unroll
;                     for (int e = 0; e < 4; ++e) { const float a = fmaxf(v0[e], 0.f), b = fmaxf(v1[e], 0.f); v0[e] = a * a; v1[e] = b * b; }
;                     u32x4 w; w.x = cvtpk(v0[0], v0[1]); w.y = cvtpk(v0[2], v0[3]); w.z = cvtpk(v1[0], v1[1]); w.w = cvtpk(v1[2], v1[3]);
;                     *(u32x4*)(rp + (size_t)bj * 2 * 256 * 64) = w; } }
	s_add_i32 s72, s72, s50
	v_lshl_add_u64 v[216:217], v[184:185], 0, s[18:19]
	s_mov_b32 m0, s72
	ds_read_b128 v[180:183], v146 offset:49152
	ds_read_b128 v[188:191], v146 offset:50176
	ds_read_b128 v[192:195], v146 offset:51200
	ds_read_b128 v[196:199], v146 offset:52224
	ds_read_b128 v[200:203], v146 offset:53248
	ds_read_b128 v[204:207], v146 offset:54272
	ds_read_b128 v[208:211], v146 offset:55296
	ds_read_b128 v[212:215], v146 offset:56320
	global_load_lds_dwordx4 v[216:217], off
	v_lshl_add_u64 v[216:217], v[184:185], 0, s[20:21]
	s_add_i32 m0, s72, 0x2000
	s_add_i32 s72, s73, s50
	global_load_lds_dwordx4 v[216:217], off
	v_lshl_add_u64 v[216:217], v[184:185], 0, s[22:23]
	s_mov_b32 m0, s72
	v_lshl_add_u64 v[184:185], v[184:185], 0, s[24:25]
	global_load_lds_dwordx4 v[216:217], off
	s_add_i32 m0, s72, 0x2000
	s_nop 0
	global_load_lds_dwordx4 v[184:185], off
	v_lshl_add_u64 v[184:185], s[46:47], 0, v[130:131]
	s_mov_b32 m0, s58
	s_nop 0
	global_load_lds_dwordx4 v[184:185], off
	v_lshl_add_u64 v[184:185], v[184:185], 0, s[10:11]
	s_mov_b32 m0, s59
	s_nop 0
	global_load_lds_dwordx4 v[184:185], off
	s_waitcnt vmcnt(8)
	s_waitcnt lgkmcnt(0)
	s_barrier
	s_setprio 1
	s_waitcnt lgkmcnt(0)
	v_mfma_f32_16x16x32_bf16 v[62:65], v[148:151], v[180:183], v[62:65]
	v_mfma_f32_16x16x32_bf16 v[58:61], v[156:159], v[180:183], v[58:61]
	v_mfma_f32_16x16x32_bf16 v[58:61], v[160:163], v[188:191], v[58:61]
	v_mfma_f32_16x16x32_bf16 v[62:65], v[152:155], v[188:191], v[62:65]
	v_mfma_f32_16x16x32_bf16 v[46:49], v[148:151], v[192:195], v[46:49]
	v_mfma_f32_16x16x32_bf16 v[42:45], v[156:159], v[192:195], v[42:45]
	v_mfma_f32_16x16x32_bf16 v[42:45], v[160:163], v[196:199], v[42:45]
	v_mfma_f32_16x16x32_bf16 v[46:49], v[152:155], v[196:199], v[46:49]
	v_mfma_f32_16x16x32_bf16 v[30:33], v[148:151], v[200:203], v[30:33]
	v_mfma_f32_16x16x32_bf16 v[26:29], v[156:159], v[200:203], v[26:29]
	v_mfma_f32_16x16x32_bf16 v[26:29], v[160:163], v[204:207], v[26:29]
	v_mfma_f32_16x16x32_bf16 v[30:33], v[152:155], v[204:207], v[30:33]
	v_mfma_f32_16x16x32_bf16 v[14:17], v[148:151], v[208:211], v[14:17]
	v_mfma_f32_16x16x32_bf16 v[10:13], v[156:159], v[208:211], v[10:13]
	v_mfma_f32_16x16x32_bf16 v[10:13], v[160:163], v[212:215], v[10:13]
	v_mfma_f32_16x16x32_bf16 v[14:17], v[152:155], v[212:215], v[14:17]
	s_setprio 0
	s_setprio 1
	v_mfma_f32_16x16x32_bf16 v[54:57], v[164:167], v[180:183], v[54:57]
	v_mfma_f32_16x16x32_bf16 v[50:53], v[172:175], v[180:183], v[50:53]
	v_mfma_f32_16x16x32_bf16 v[50:53], v[176:179], v[188:191], v[50:53]
	v_mfma_f32_16x16x32_bf16 v[54:57], v[168:171], v[188:191], v[54:57]
	v_mfma_f32_16x16x32_bf16 v[38:41], v[164:167], v[192:195], v[38:41]
	v_mfma_f32_16x16x32_bf16 v[34:37], v[172:175], v[192:195], v[34:37]
	v_mfma_f32_16x16x32_bf16 v[34:37], v[176:179], v[196:199], v[34:37]
	v_mfma_f32_16x16x32_bf16 v[38:41], v[168:171], v[196:199], v[38:41]
	v_mfma_f32_16x16x32_bf16 v[22:25], v[164:167], v[200:203], v[22:25]
	v_mfma_f32_16x16x32_bf16 v[18:21], v[172:175], v[200:203], v[18:21]
	v_mfma_f32_16x16x32_bf16 v[18:21], v[176:179], v[204:207], v[18:21]
	v_mfma_f32_16x16x32_bf16 v[22:25], v[168:171], v[204:207], v[22:25]
	v_mfma_f32_16x16x32_bf16 v[6:9], v[164:167], v[208:211], v[6:9]
	v_mfma_f32_16x16x32_bf16 v[2:5], v[172:175], v[208:211], v[2:5]
	v_mfma_f32_16x16x32_bf16 v[2:5], v[176:179], v[212:215], v[2:5]
	v_mfma_f32_16x16x32_bf16 v[6:9], v[168:171], v[212:215], v[6:9]
	s_setprio 0
	s_barrier
	s_add_i32 s71, s71, 2
	s_add_u32 s69, s69, 0x100
	s_addc_u32 s70, s70, 0
	s_add_u32 s44, s44, 0x10000
	s_addc_u32 s45, s45, 0
	s_cmp_gt_u32 s71, 61
	s_cbranch_scc0 .LBB0_1206
	s_lshl_b32 s29, s41, 2
	s_or_b32 s42, s29, s61
	s_ashr_i32 s41, s40, 31
	s_ashr_i32 s43, s42, 31
	s_lshl_b64 s[40:41], s[40:41], 16
	s_lshl_b64 s[42:43], s[42:43], 8
	s_add_u32 s40, s42, s40
	v_lshrrev_b32_e32 v142, 1, v147
	s_addc_u32 s41, s43, s41
	v_and_b32_e32 v150, 56, v142
	v_lshl_add_u64 v[142:143], s[40:41], 0, v[134:135]
	v_max_f32_e32 v122, v122, v122
	v_max_f32_e32 v123, v123, v123
	v_lshlrev_b64 v[142:143], 7, v[142:143]
	v_max_f32_e32 v122, 0, v122
	v_max_f32_e32 v123, 0, v123
	v_lshl_add_u64 v[148:149], s[16:17], 0, v[142:143]
	v_add_lshl_u32 v142, v150, s62, 1
	v_pk_mul_f32 v[150:151], v[122:123], v[122:123]
	v_max_f32_e32 v123, v124, v124
	v_max_f32_e32 v126, v126, v126
	v_max_f32_e32 v127, v127, v127
	v_max_f32_e32 v122, v128, v128
	v_max_f32_e32 v124, 0, v123
	v_max_f32_e32 v123, v129, v129
	v_max_f32_e32 v125, v125, v125
	v_max_f32_e32 v126, 0, v126
	v_max_f32_e32 v127, 0, v127
	v_max_f32_e32 v122, 0, v122
	v_max_f32_e32 v123, 0, v123
	v_max_f32_e32 v125, 0, v125
	v_mov_b32_e32 v143, v135
	v_pk_mul_f32 v[126:127], v[126:127], v[126:127]
	v_pk_mul_f32 v[128:129], v[122:123], v[122:123]
	v_pk_mul_f32 v[152:153], v[124:125], v[124:125]
	v_max_f32_e32 v114, v114, v114
	v_max_f32_e32 v115, v115, v115
	v_lshl_add_u64 v[148:149], v[148:149], 0, v[142:143]
	v_cvt_pk_bf16_f32 v122, v126, v127
	v_cvt_pk_bf16_f32 v123, v128, v129
	v_cvt_pk_bf16_f32 v124, v150, v151
	v_cvt_pk_bf16_f32 v125, v152, v153
	v_max_f32_e32 v114, 0, v114
	v_max_f32_e32 v115, 0, v115
	global_store_dwordx4 v[148:149], v[122:125], off nt
	v_max_f32_e32 v118, v118, v118
	v_max_f32_e32 v119, v119, v119
	v_pk_mul_f32 v[122:123], v[114:115], v[114:115]
	v_max_f32_e32 v115, v116, v116
	v_max_f32_e32 v118, 0, v118
	v_max_f32_e32 v119, 0, v119
	v_max_f32_e32 v114, v120, v120
	v_max_f32_e32 v116, 0, v115
	v_max_f32_e32 v115, v121, v121
	v_max_f32_e32 v117, v117, v117
	v_pk_mul_f32 v[118:119], v[118:119], v[118:119]
	v_max_f32_e32 v114, 0, v114
	v_max_f32_e32 v115, 0, v115
	v_max_f32_e32 v117, 0, v117
; __device__ __forceinline__ unsigned cvtpk(float lo, float hi) { f32x2 v = {lo, hi}; bf16x2_t b = __builtin_convertvector(v, bf16x2_t); return __builtin_bit_cast(unsigned, b); }
;     __device__ __forceinline__ void operator()(const Acc& acc, const Unit& u, int wr, int wc, int fr, int fq) const {
;     ...
;         const int rl = wr * 64 + fr, kt0 = u.pn * 4 + (wc >> 1), cl = (wc & 1) * 32 + 8 * fq;
; #pragma unroll
;         for (int ai = 0; ai < 2; ++ai)
; #pragma unroll
;             for (int m = 0; m < 4; ++m) { bf16_t* rp = O + (((size_t)u.pm * (DFF / 64) + kt0) * 256 + (rl + ai * 128 + m * 16)) * 64 + cl;
; #pragma unroll
;                 for (int bj = 0; bj < 2; ++bj) { f32x4 v0 = acc[ai][bj][m][0], v1 = acc[ai][bj][m][1];
; #pragma unroll
;                     for (int e = 0; e < 4; ++e) { const float a = fmaxf(v0[e], 0.f), b = fmaxf(v1[e], 0.f); v0[e] = a * a; v1[e] = b * b; }
;                     u32x4 w; w.x = cvtpk(v0[0], v0[1]); w.y = cvtpk(v0[2], v0[3]); w.z = cvtpk(v1[0], v1[1]); w.w = cvtpk(v1[2], v1[3]);
;                     *(u32x4*)(rp + (size_t)bj * 2 * 256 * 64) = w; } }
	v_pk_mul_f32 v[120:121], v[114:115], v[114:115]
	v_pk_mul_f32 v[124:125], v[116:117], v[116:117]
	v_cvt_pk_bf16_f32 v114, v118, v119
	v_add_co_u32_e32 v118, vcc, s57, v148
	v_max_f32_e32 v106, v106, v106
	v_max_f32_e32 v107, v107, v107
	v_cvt_pk_bf16_f32 v115, v120, v121
	v_cvt_pk_bf16_f32 v116, v122, v123
	v_cvt_pk_bf16_f32 v117, v124, v125
	v_addc_co_u32_e32 v119, vcc, 0, v149, vcc
	v_max_f32_e32 v106, 0, v106
	v_max_f32_e32 v107, 0, v107
	global_store_dwordx4 v[118:119], v[114:117], off nt
	v_max_f32_e32 v110, v110, v110
	v_max_f32_e32 v111, v111, v111
	v_or_b32_e32 v114, 16, v134
	v_mov_b32_e32 v115, v135
	v_pk_mul_f32 v[116:117], v[106:107], v[106:107]
	v_max_f32_e32 v107, v108, v108
	v_lshl_add_u64 v[114:115], s[40:41], 0, v[114:115]
	v_max_f32_e32 v106, v112, v112
	v_max_f32_e32 v108, 0, v107
	v_max_f32_e32 v107, v113, v113
	v_max_f32_e32 v109, v109, v109
	v_lshlrev_b64 v[114:115], 7, v[114:115]
	v_max_f32_e32 v110, 0, v110
	v_max_f32_e32 v111, 0, v111
	v_max_f32_e32 v106, 0, v106
	v_max_f32_e32 v107, 0, v107
	v_max_f32_e32 v109, 0, v109
	v_lshl_add_u64 v[114:115], s[16:17], 0, v[114:115]
	v_pk_mul_f32 v[110:111], v[110:111], v[110:111]
	v_pk_mul_f32 v[112:113], v[106:107], v[106:107]
	v_pk_mul_f32 v[118:119], v[108:109], v[108:109]
	v_max_f32_e32 v98, v98, v98
	v_max_f32_e32 v99, v99, v99
	v_lshl_add_u64 v[114:115], v[114:115], 0, v[142:143]
	v_cvt_pk_bf16_f32 v106, v110, v111
	v_cvt_pk_bf16_f32 v107, v112, v113
	v_cvt_pk_bf16_f32 v108, v116, v117
	v_cvt_pk_bf16_f32 v109, v118, v119
	v_max_f32_e32 v98, 0, v98
	v_max_f32_e32 v99, 0, v99
	global_store_dwordx4 v[114:115], v[106:109], off nt
	v_max_f32_e32 v102, v102, v102
	v_max_f32_e32 v103, v103, v103
	v_pk_mul_f32 v[106:107], v[98:99], v[98:99]
	v_max_f32_e32 v99, v100, v100
	v_max_f32_e32 v102, 0, v102
	v_max_f32_e32 v103, 0, v103
	v_max_f32_e32 v98, v104, v104
	v_max_f32_e32 v100, 0, v99
	v_max_f32_e32 v99, v105, v105
	v_max_f32_e32 v101, v101, v101
	v_pk_mul_f32 v[102:103], v[102:103], v[102:103]
	v_max_f32_e32 v98, 0, v98
	v_max_f32_e32 v99, 0, v99
	v_max_f32_e32 v101, 0, v101
	v_pk_mul_f32 v[104:105], v[98:99], v[98:99]
	v_pk_mul_f32 v[108:109], v[100:101], v[100:101]
	v_cvt_pk_bf16_f32 v98, v102, v103
	v_add_co_u32_e32 v102, vcc, s57, v114
	v_max_f32_e32 v90, v90, v90
	v_max_f32_e32 v91, v91, v91
	v_cvt_pk_bf16_f32 v99, v104, v105
	v_cvt_pk_bf16_f32 v100, v106, v107
	v_cvt_pk_bf16_f32 v101, v108, v109
	v_addc_co_u32_e32 v103, vcc, 0, v115, vcc
	v_max_f32_e32 v90, 0, v90
	v_max_f32_e32 v91, 0, v91
	global_store_dwordx4 v[102:103], v[98:101], off nt
	v_max_f32_e32 v94, v94, v94
	v_max_f32_e32 v95, v95, v95
	v_or_b32_e32 v98, 32, v134
	v_mov_b32_e32 v99, v135
	v_pk_mul_f32 v[100:101], v[90:91], v[90:91]
	v_max_f32_e32 v91, v92, v92
	v_lshl_add_u64 v[98:99], s[40:41], 0, v[98:99]
	v_max_f32_e32 v90, v96, v96
	v_max_f32_e32 v92, 0, v91
	v_max_f32_e32 v91, v97, v97
	v_max_f32_e32 v93, v93, v93
	v_lshlrev_b64 v[98:99], 7, v[98:99]
	v_max_f32_e32 v94, 0, v94
	v_max_f32_e32 v95, 0, v95
	v_max_f32_e32 v90, 0, v90
	v_max_f32_e32 v91, 0, v91
	v_max_f32_e32 v93, 0, v93
	v_lshl_add_u64 v[98:99], s[16:17], 0, v[98:99]
	v_pk_mul_f32 v[94:95], v[94:95], v[94:95]
	v_pk_mul_f32 v[96:97], v[90:91], v[90:91]
	v_pk_mul_f32 v[102:103], v[92:93], v[92:93]
	v_max_f32_e32 v82, v82, v82
	v_max_f32_e32 v83, v83, v83
	v_lshl_add_u64 v[98:99], v[98:99], 0, v[142:143]
	v_cvt_pk_bf16_f32 v90, v94, v95
	v_cvt_pk_bf16_f32 v91, v96, v97
	v_cvt_pk_bf16_f32 v92, v100, v101
	v_cvt_pk_bf16_f32 v93, v102, v103
	v_max_f32_e32 v82, 0, v82
	v_max_f32_e32 v83, 0, v83
	global_store_dwordx4 v[98:99], v[90:93], off nt
	v_max_f32_e32 v86, v86, v86
	v_max_f32_e32 v87, v87, v87
	v_pk_mul_f32 v[90:91], v[82:83], v[82:83]
	v_max_f32_e32 v83, v84, v84
	v_max_f32_e32 v86, 0, v86
	v_max_f32_e32 v87, 0, v87
	v_max_f32_e32 v82, v88, v88
	v_max_f32_e32 v84, 0, v83
	v_max_f32_e32 v83, v89, v89
	v_max_f32_e32 v85, v85, v85
	v_pk_mul_f32 v[86:87], v[86:87], v[86:87]
	v_max_f32_e32 v82, 0, v82
	v_max_f32_e32 v83, 0, v83
	v_max_f32_e32 v85, 0, v85
	v_pk_mul_f32 v[88:89], v[82:83], v[82:83]
	v_pk_mul_f32 v[92:93], v[84:85], v[84:85]
	v_cvt_pk_bf16_f32 v82, v86, v87
	v_add_co_u32_e32 v86, vcc, s57, v98
	v_max_f32_e32 v74, v74, v74
	v_max_f32_e32 v75, v75, v75
	v_cvt_pk_bf16_f32 v83, v88, v89
	v_cvt_pk_bf16_f32 v84, v90, v91
	v_cvt_pk_bf16_f32 v85, v92, v93
	v_addc_co_u32_e32 v87, vcc, 0, v99, vcc
	v_max_f32_e32 v74, 0, v74
	v_max_f32_e32 v75, 0, v75
	global_store_dwordx4 v[86:87], v[82:85], off nt
	v_max_f32_e32 v78, v78, v78
	v_max_f32_e32 v79, v79, v79
	v_or_b32_e32 v82, 48, v134
	v_mov_b32_e32 v83, v135
	v_pk_mul_f32 v[84:85], v[74:75], v[74:75]
	v_max_f32_e32 v75, v76, v76
	v_lshl_add_u64 v[82:83], s[40:41], 0, v[82:83]
	v_max_f32_e32 v74, v80, v80
	v_max_f32_e32 v76, 0, v75
	v_max_f32_e32 v75, v81, v81
	v_max_f32_e32 v77, v77, v77
	v_lshlrev_b64 v[82:83], 7, v[82:83]
	v_max_f32_e32 v78, 0, v78
	v_max_f32_e32 v79, 0, v79
	v_max_f32_e32 v74, 0, v74
	v_max_f32_e32 v75, 0, v75
	v_max_f32_e32 v77, 0, v77
	v_lshl_add_u64 v[82:83], s[16:17], 0, v[82:83]
	v_pk_mul_f32 v[78:79], v[78:79], v[78:79]
	v_pk_mul_f32 v[80:81], v[74:75], v[74:75]
	v_pk_mul_f32 v[86:87], v[76:77], v[76:77]
	v_max_f32_e32 v66, v66, v66
	v_max_f32_e32 v67, v67, v67
	v_lshl_add_u64 v[82:83], v[82:83], 0, v[142:143]
	v_cvt_pk_bf16_f32 v74, v78, v79
	v_cvt_pk_bf16_f32 v75, v80, v81
	v_cvt_pk_bf16_f32 v76, v84, v85
	v_cvt_pk_bf16_f32 v77, v86, v87
	v_max_f32_e32 v66, 0, v66
	v_max_f32_e32 v67, 0, v67
	global_store_dwordx4 v[82:83], v[74:77], off nt
	v_max_f32_e32 v70, v70, v70
	v_max_f32_e32 v71, v71, v71
	v_pk_mul_f32 v[74:75], v[66:67], v[66:67]
	v_max_f32_e32 v67, v68, v68
; __device__ __forceinline__ unsigned cvtpk(float lo, float hi) { f32x2 v = {lo, hi}; bf16x2_t b = __builtin_convertvector(v, bf16x2_t); return __builtin_bit_cast(unsigned, b); }
;     __device__ __forceinline__ void operator()(const Acc& acc, const Unit& u, int wr, int wc, int fr, int fq) const {
;     ...
;         const int rl = wr * 64 + fr, kt0 = u.pn * 4 + (wc >> 1), cl = (wc & 1) * 32 + 8 * fq;
; #pragma unroll
;         for (int ai = 0; ai < 2; ++ai)
; #pragma unroll
;             for (int m = 0; m < 4; ++m) { bf16_t* rp = O + (((size_t)u.pm * (DFF / 64) + kt0) * 256 + (rl + ai * 128 + m * 16)) * 64 + cl;
; #pragma unroll
;                 for (int bj = 0; bj < 2; ++bj) { f32x4 v0 = acc[ai][bj][m][0], v1 = acc[ai][bj][m][1];
; #pragma unroll
;                     for (int e = 0; e < 4; ++e) { const float a = fmaxf(v0[e], 0.f), b = fmaxf(v1[e], 0.f); v0[e] = a * a; v1[e] = b * b; }
;                     u32x4 w; w.x = cvtpk(v0[0], v0[1]); w.y = cvtpk(v0[2], v0[3]); w.z = cvtpk(v1[0], v1[1]); w.w = cvtpk(v1[2], v1[3]);
;                     *(u32x4*)(rp + (size_t)bj * 2 * 256 * 64) = w; } }
	v_max_f32_e32 v70, 0, v70
	v_max_f32_e32 v71, 0, v71
	v_max_f32_e32 v66, v72, v72
	v_max_f32_e32 v68, 0, v67
	v_max_f32_e32 v67, v73, v73
	v_max_f32_e32 v69, v69, v69
	v_pk_mul_f32 v[70:71], v[70:71], v[70:71]
	v_max_f32_e32 v66, 0, v66
	v_max_f32_e32 v67, 0, v67
	v_max_f32_e32 v69, 0, v69
	v_pk_mul_f32 v[72:73], v[66:67], v[66:67]
	v_pk_mul_f32 v[76:77], v[68:69], v[68:69]
	v_cvt_pk_bf16_f32 v66, v70, v71
	v_add_co_u32_e32 v70, vcc, s57, v82
	v_max_f32_e32 v58, v58, v58
	v_max_f32_e32 v59, v59, v59
	v_cvt_pk_bf16_f32 v67, v72, v73
	v_cvt_pk_bf16_f32 v68, v74, v75
	v_cvt_pk_bf16_f32 v69, v76, v77
	v_addc_co_u32_e32 v71, vcc, 0, v83, vcc
	v_max_f32_e32 v58, 0, v58
	v_max_f32_e32 v59, 0, v59
	global_store_dwordx4 v[70:71], v[66:69], off nt
	v_max_f32_e32 v62, v62, v62
	v_max_f32_e32 v63, v63, v63
	v_add_u32_e32 v66, 0x80, v134
	v_mov_b32_e32 v67, v135
	v_pk_mul_f32 v[68:69], v[58:59], v[58:59]
	v_max_f32_e32 v59, v60, v60
	v_lshl_add_u64 v[66:67], s[40:41], 0, v[66:67]
	v_max_f32_e32 v58, v64, v64
	v_max_f32_e32 v60, 0, v59
	v_max_f32_e32 v59, v65, v65
	v_max_f32_e32 v61, v61, v61
	v_lshlrev_b64 v[66:67], 7, v[66:67]
	v_max_f32_e32 v62, 0, v62
	v_max_f32_e32 v63, 0, v63
	v_max_f32_e32 v58, 0, v58
	v_max_f32_e32 v59, 0, v59
	v_max_f32_e32 v61, 0, v61
	v_lshl_add_u64 v[66:67], s[16:17], 0, v[66:67]
	v_pk_mul_f32 v[62:63], v[62:63], v[62:63]
	v_pk_mul_f32 v[64:65], v[58:59], v[58:59]
	v_pk_mul_f32 v[70:71], v[60:61], v[60:61]
	v_max_f32_e32 v50, v50, v50
	v_max_f32_e32 v51, v51, v51
	v_lshl_add_u64 v[66:67], v[66:67], 0, v[142:143]
	v_cvt_pk_bf16_f32 v58, v62, v63
	v_cvt_pk_bf16_f32 v59, v64, v65
	v_cvt_pk_bf16_f32 v60, v68, v69
	v_cvt_pk_bf16_f32 v61, v70, v71
	v_max_f32_e32 v50, 0, v50
	v_max_f32_e32 v51, 0, v51
	global_store_dwordx4 v[66:67], v[58:61], off nt
	v_max_f32_e32 v54, v54, v54
	v_max_f32_e32 v55, v55, v55
	v_pk_mul_f32 v[58:59], v[50:51], v[50:51]
	v_max_f32_e32 v51, v52, v52
	v_max_f32_e32 v54, 0, v54
	v_max_f32_e32 v55, 0, v55
	v_max_f32_e32 v50, v56, v56
	v_max_f32_e32 v52, 0, v51
	v_max_f32_e32 v51, v57, v57
	v_max_f32_e32 v53, v53, v53
	v_pk_mul_f32 v[54:55], v[54:55], v[54:55]
	v_max_f32_e32 v50, 0, v50
	v_max_f32_e32 v51, 0, v51
	v_max_f32_e32 v53, 0, v53
	v_pk_mul_f32 v[56:57], v[50:51], v[50:51]
	v_pk_mul_f32 v[60:61], v[52:53], v[52:53]
	v_cvt_pk_bf16_f32 v50, v54, v55
	v_add_co_u32_e32 v54, vcc, s57, v66
	v_max_f32_e32 v42, v42, v42
	v_max_f32_e32 v43, v43, v43
	v_cvt_pk_bf16_f32 v51, v56, v57
	v_cvt_pk_bf16_f32 v52, v58, v59
	v_cvt_pk_bf16_f32 v53, v60, v61
	v_addc_co_u32_e32 v55, vcc, 0, v67, vcc
	v_max_f32_e32 v42, 0, v42
	v_max_f32_e32 v43, 0, v43
	global_store_dwordx4 v[54:55], v[50:53], off nt
	v_max_f32_e32 v46, v46, v46
	v_max_f32_e32 v47, v47, v47
	v_add_u32_e32 v50, 0x90, v134
	v_mov_b32_e32 v51, v135
	v_pk_mul_f32 v[52:53], v[42:43], v[42:43]
	v_max_f32_e32 v43, v44, v44
	v_lshl_add_u64 v[50:51], s[40:41], 0, v[50:51]
	v_max_f32_e32 v42, v48, v48
	v_max_f32_e32 v44, 0, v43
	v_max_f32_e32 v43, v49, v49
	v_max_f32_e32 v45, v45, v45
	v_lshlrev_b64 v[50:51], 7, v[50:51]
	v_max_f32_e32 v46, 0, v46
	v_max_f32_e32 v47, 0, v47
	v_max_f32_e32 v42, 0, v42
	v_max_f32_e32 v43, 0, v43
	v_max_f32_e32 v45, 0, v45
	v_lshl_add_u64 v[50:51], s[16:17], 0, v[50:51]
	v_pk_mul_f32 v[46:47], v[46:47], v[46:47]
	v_pk_mul_f32 v[48:49], v[42:43], v[42:43]
	v_pk_mul_f32 v[54:55], v[44:45], v[44:45]
	v_max_f32_e32 v34, v34, v34
	v_max_f32_e32 v35, v35, v35
	v_lshl_add_u64 v[50:51], v[50:51], 0, v[142:143]
	v_cvt_pk_bf16_f32 v42, v46, v47
	v_cvt_pk_bf16_f32 v43, v48, v49
	v_cvt_pk_bf16_f32 v44, v52, v53
	v_cvt_pk_bf16_f32 v45, v54, v55
	v_max_f32_e32 v34, 0, v34
	v_max_f32_e32 v35, 0, v35
	global_store_dwordx4 v[50:51], v[42:45], off nt
	v_max_f32_e32 v38, v38, v38
	v_max_f32_e32 v39, v39, v39
	v_pk_mul_f32 v[42:43], v[34:35], v[34:35]
	v_max_f32_e32 v35, v36, v36
	v_max_f32_e32 v38, 0, v38
	v_max_f32_e32 v39, 0, v39
	v_max_f32_e32 v34, v40, v40
	v_max_f32_e32 v36, 0, v35
	v_max_f32_e32 v35, v41, v41
	v_max_f32_e32 v37, v37, v37
	v_pk_mul_f32 v[38:39], v[38:39], v[38:39]
	v_max_f32_e32 v34, 0, v34
	v_max_f32_e32 v35, 0, v35
	v_max_f32_e32 v37, 0, v37
	v_pk_mul_f32 v[40:41], v[34:35], v[34:35]
	v_pk_mul_f32 v[44:45], v[36:37], v[36:37]
	v_cvt_pk_bf16_f32 v34, v38, v39
; __device__ __forceinline__ unsigned cvtpk(float lo, float hi) { f32x2 v = {lo, hi}; bf16x2_t b = __builtin_convertvector(v, bf16x2_t); return __builtin_bit_cast(unsigned, b); }
; #define PG8_WAIT_V(n) asm volatile("s_waitcnt vmcnt(" #n ")" ::: "memory")
; #define PG8_BAR __builtin_amdgcn_s_barrier()
;     ...
;         if (!has_next) break;
; #pragma unroll
;         for (int a = 0; a < 2; ++a)
; #pragma unroll
;             for (int b = 0; b < 2; ++b)
; #pragma unroll
;                 for (int m = 0; m < 4; ++m)
; #pragma unroll
;                     for (int n = 0; n < 2; ++n) acc[a][b][m][n] = (f32x4){0.f, 0.f, 0.f, 0.f};
;         cur = nxt; cA = nA; cB = nB; ++ui;
;         if constexpr (ALIGN) { if (wr == 1) PG8_BAR; }
;     }
;     PG8_WAIT_V(0);
;     if constexpr (!ALIGN) { if (wr == 0) PG8_BAR; }
;     PG8_BAR;
;     __device__ __forceinline__ void operator()(const Acc& acc, const Unit& u, int wr, int wc, int fr, int fq) const {
;     ...
;         const int rl = wr * 64 + fr, kt0 = u.pn * 4 + (wc >> 1), cl = (wc & 1) * 32 + 8 * fq;
; #pragma unroll
;         for (int ai = 0; ai < 2; ++ai)
; #pragma unroll
;             for (int m = 0; m < 4; ++m) { bf16_t* rp = O + (((size_t)u.pm * (DFF / 64) + kt0) * 256 + (rl + ai * 128 + m * 16)) * 64 + cl;
; #pragma unroll
;                 for (int bj = 0; bj < 2; ++bj) { f32x4 v0 = acc[ai][bj][m][0], v1 = acc[ai][bj][m][1];
; #pragma unroll
;                     for (int e = 0; e < 4; ++e) { const float a = fmaxf(v0[e], 0.f), b = fmaxf(v1[e], 0.f); v0[e] = a * a; v1[e] = b * b; }
;                     u32x4 w; w.x = cvtpk(v0[0], v0[1]); w.y = cvtpk(v0[2], v0[3]); w.z = cvtpk(v1[0], v1[1]); w.w = cvtpk(v1[2], v1[3]);
;                     *(u32x4*)(rp + (size_t)bj * 2 * 256 * 64) = w; } }
	v_add_co_u32_e32 v38, vcc, s57, v50
	v_max_f32_e32 v26, v26, v26
	v_max_f32_e32 v27, v27, v27
	v_cvt_pk_bf16_f32 v35, v40, v41
	v_cvt_pk_bf16_f32 v36, v42, v43
	v_cvt_pk_bf16_f32 v37, v44, v45
	v_addc_co_u32_e32 v39, vcc, 0, v51, vcc
	v_max_f32_e32 v26, 0, v26
	v_max_f32_e32 v27, 0, v27
	global_store_dwordx4 v[38:39], v[34:37], off nt
	v_max_f32_e32 v30, v30, v30
	v_max_f32_e32 v31, v31, v31
	v_add_u32_e32 v34, 0xa0, v134
	v_mov_b32_e32 v35, v135
	v_pk_mul_f32 v[36:37], v[26:27], v[26:27]
	v_max_f32_e32 v27, v28, v28
	v_lshl_add_u64 v[34:35], s[40:41], 0, v[34:35]
	v_max_f32_e32 v26, v32, v32
	v_max_f32_e32 v28, 0, v27
	v_max_f32_e32 v27, v33, v33
	v_max_f32_e32 v29, v29, v29
	v_lshlrev_b64 v[34:35], 7, v[34:35]
	v_max_f32_e32 v30, 0, v30
	v_max_f32_e32 v31, 0, v31
	v_max_f32_e32 v26, 0, v26
	v_max_f32_e32 v27, 0, v27
	v_max_f32_e32 v29, 0, v29
	v_lshl_add_u64 v[34:35], s[16:17], 0, v[34:35]
	v_pk_mul_f32 v[30:31], v[30:31], v[30:31]
	v_pk_mul_f32 v[32:33], v[26:27], v[26:27]
	v_pk_mul_f32 v[38:39], v[28:29], v[28:29]
	v_max_f32_e32 v18, v18, v18
	v_max_f32_e32 v19, v19, v19
	v_lshl_add_u64 v[34:35], v[34:35], 0, v[142:143]
	v_cvt_pk_bf16_f32 v26, v30, v31
	v_cvt_pk_bf16_f32 v27, v32, v33
	v_cvt_pk_bf16_f32 v28, v36, v37
	v_cvt_pk_bf16_f32 v29, v38, v39
	v_max_f32_e32 v18, 0, v18
	v_max_f32_e32 v19, 0, v19
	global_store_dwordx4 v[34:35], v[26:29], off nt
	v_max_f32_e32 v22, v22, v22
	v_max_f32_e32 v23, v23, v23
	v_pk_mul_f32 v[26:27], v[18:19], v[18:19]
	v_max_f32_e32 v19, v20, v20
	v_max_f32_e32 v22, 0, v22
	v_max_f32_e32 v23, 0, v23
	v_max_f32_e32 v18, v24, v24
	v_max_f32_e32 v20, 0, v19
	v_max_f32_e32 v19, v25, v25
	v_max_f32_e32 v21, v21, v21
	v_pk_mul_f32 v[22:23], v[22:23], v[22:23]
	v_max_f32_e32 v18, 0, v18
	v_max_f32_e32 v19, 0, v19
	v_max_f32_e32 v21, 0, v21
	v_pk_mul_f32 v[24:25], v[18:19], v[18:19]
	v_pk_mul_f32 v[28:29], v[20:21], v[20:21]
	v_cvt_pk_bf16_f32 v18, v22, v23
	v_add_co_u32_e32 v22, vcc, s57, v34
	v_max_f32_e32 v10, v10, v10
	v_max_f32_e32 v11, v11, v11
	v_cvt_pk_bf16_f32 v19, v24, v25
	v_cvt_pk_bf16_f32 v20, v26, v27
	v_cvt_pk_bf16_f32 v21, v28, v29
	v_addc_co_u32_e32 v23, vcc, 0, v35, vcc
	v_max_f32_e32 v10, 0, v10
	v_max_f32_e32 v11, 0, v11
	global_store_dwordx4 v[22:23], v[18:21], off nt
	v_max_f32_e32 v14, v14, v14
	v_max_f32_e32 v15, v15, v15
	v_add_u32_e32 v18, 0xb0, v134
	v_mov_b32_e32 v19, v135
	v_pk_mul_f32 v[20:21], v[10:11], v[10:11]
	v_max_f32_e32 v11, v12, v12
	v_lshl_add_u64 v[18:19], s[40:41], 0, v[18:19]
	v_max_f32_e32 v10, v16, v16
	v_max_f32_e32 v12, 0, v11
	v_max_f32_e32 v11, v17, v17
	v_max_f32_e32 v13, v13, v13
	v_lshlrev_b64 v[18:19], 7, v[18:19]
	v_max_f32_e32 v14, 0, v14
	v_max_f32_e32 v15, 0, v15
	v_max_f32_e32 v10, 0, v10
	v_max_f32_e32 v11, 0, v11
	v_max_f32_e32 v13, 0, v13
	v_lshl_add_u64 v[18:19], s[16:17], 0, v[18:19]
	v_pk_mul_f32 v[14:15], v[14:15], v[14:15]
	v_pk_mul_f32 v[16:17], v[10:11], v[10:11]
	v_pk_mul_f32 v[22:23], v[12:13], v[12:13]
	v_max_f32_e32 v2, v2, v2
	v_max_f32_e32 v3, v3, v3
	v_lshl_add_u64 v[18:19], v[18:19], 0, v[142:143]
	v_cvt_pk_bf16_f32 v10, v14, v15
	v_cvt_pk_bf16_f32 v11, v16, v17
	v_cvt_pk_bf16_f32 v12, v20, v21
	v_cvt_pk_bf16_f32 v13, v22, v23
	v_max_f32_e32 v2, 0, v2
	v_max_f32_e32 v3, 0, v3
	global_store_dwordx4 v[18:19], v[10:13], off nt
	v_max_f32_e32 v6, v6, v6
	v_max_f32_e32 v7, v7, v7
	v_pk_mul_f32 v[10:11], v[2:3], v[2:3]
	v_max_f32_e32 v3, v4, v4
	v_max_f32_e32 v6, 0, v6
	v_max_f32_e32 v7, 0, v7
	v_max_f32_e32 v2, v8, v8
	v_max_f32_e32 v4, 0, v3
	v_max_f32_e32 v3, v9, v9
	v_pk_mul_f32 v[6:7], v[6:7], v[6:7]
	v_max_f32_e32 v2, 0, v2
	v_max_f32_e32 v3, 0, v3
	v_max_f32_e32 v5, v5, v5
	v_max_f32_e32 v5, 0, v5
	v_pk_mul_f32 v[8:9], v[2:3], v[2:3]
	v_cvt_pk_bf16_f32 v2, v6, v7
	v_add_co_u32_e32 v6, vcc, 0x10000, v18
	v_pk_mul_f32 v[12:13], v[4:5], v[4:5]
	s_nop 0
	v_addc_co_u32_e32 v7, vcc, 0, v19, vcc
	v_cvt_pk_bf16_f32 v3, v8, v9
	v_cvt_pk_bf16_f32 v4, v10, v11
	v_cvt_pk_bf16_f32 v5, v12, v13
	s_and_b64 vcc, exec, s[2:3]
	s_mov_b32 s41, s28
	s_mov_b32 s40, s34
	s_mov_b64 s[44:45], s[38:39]
	s_mov_b64 s[42:43], s[36:37]
	global_store_dwordx4 v[6:7], v[2:5], off nt
	s_cbranch_vccz .LBB0_1199
	s_waitcnt vmcnt(0)
	s_cmpk_gt_u32 s33, 0xff
	s_cbranch_scc1 .LBB0_1210
	s_barrier

;     __device__ __forceinline__ size_t a_koff(int t) const { return (size_t)t * 128; }
;     __device__ __forceinline__ size_t a_koff(int t) const { return (size_t)t * 32768; }
; #define PG8_STAGE(bufoff, gbase, voff) do { _Pragma("unroll") for (int _i = 0; _i < 2; ++_i) \
;         __builtin_amdgcn_global_load_lds((const unsigned*)((const char*)(gbase) + (size_t)_i * p##voff + (voff)), (LAS unsigned*)(lds + (bufoff) + ldsw + _i * 8192), 16, 0, 0); } while (0)
; #define PG8_LDA(dst, b, h) do { _Pragma("unroll") for (int m = 0; m < 4; ++m) _Pragma("unroll") for (int k = 0; k < 2; ++k) dst[m][k] = *(const LAS bf16x8*)(lds + PG8_SA(b, h) + aoff + m * 2048 + k * 1024); } while (0)
; #define PG8_LDB(dst, b, h) do { _Pragma("unroll") for (int n = 0; n < 2; ++n) _Pragma("unroll") for (int k = 0; k < 2; ++k) dst[n][k] = *(const LAS bf16x8*)(lds + PG8_SB(b, h) + boff + n * 2048 + k * 1024); } while (0)
; #define PG8_WAIT_V(n) asm volatile("s_waitcnt vmcnt(" #n ")" ::: "memory")
; #define PG8_WAIT_L(n) asm volatile("s_waitcnt lgkmcnt(" #n ")" ::: "memory")
; #define PG8_BAR __builtin_amdgcn_s_barrier()
; #define PG8_SCHED __builtin_amdgcn_sched_barrier(0)
;     __device__ __forceinline__ size_t a_koff(int t) const { return ((size_t)(t >> 1) * 3072 + (size_t)(t & 1) * 64) * 2; }
;     __device__ __forceinline__ size_t a_koff(int t) const { return (size_t)t * 128; }
;     ...
;         for (int t = 0; t < nt; t += 2) {
;             const bool last = (t == nt - 2);
;             const char* a1 = cA + g.a_koff(t + 1);
;             const char* a2 = last ? nA : cA + g.a_koff(t + 2); const char* b2 = last ? nB : cB + (size_t)(t + 2) * kstep;
;             const char* a3 = last ? nA + g.a_koff(1) : cA + g.a_koff(t + 3); const char* b3 = b2 + kstep;
;             PG8_LDB(B0, 0, 0); PG8_LDB(B1, 0, 1); PG8_SCHED; PG8_LDA(At, 0, 0); PG8_STAGE(PG8_SA(1, 1), a1 + hstepA, voffA);
;             PG8_WAIT_V(8); PG8_WAIT_L(0); PG8_BAR; PG8_MMA(0, 0, At, B0); PG8_MMA(0, 1, At, B1); PG8_BAR; PG8_SCHED;
;             PG8_LDA(At, 0, 1); PG8_STAGE(PG8_SB(0, 0), b2, voffB); PG8_STAGE(PG8_SB(0, 1), b2 + hstepB, voffB); PG8_STAGE(PG8_SA(0, 0), a2, voffA);
;             PG8_WAIT_V(8); PG8_WAIT_L(0); PG8_BAR; PG8_MMA(1, 0, At, B0); PG8_MMA(1, 1, At, B1); PG8_BAR; PG8_SCHED;
.LBB0_1281:
	ds_read_b128 v[142:145], v188
	ds_read_b128 v[146:149], v188 offset:1024
	ds_read_b128 v[150:153], v188 offset:2048
	ds_read_b128 v[154:157], v188 offset:3072
	ds_read_b128 v[158:161], v189
	ds_read_b128 v[162:165], v189 offset:1024
	ds_read_b128 v[166:169], v189 offset:2048
	ds_read_b128 v[170:173], v189 offset:3072
	s_add_u32 s50, s44, s48
	s_addc_u32 s51, s45, s49
	s_add_u32 s83, s50, 0x10000
	s_addc_u32 s86, s51, 0
	s_add_u32 s50, s50, 0x18000
	s_addc_u32 s51, s51, 0
	s_cmp_eq_u32 s48, 0x7f0000
	s_cselect_b32 s51, s79, s51
	s_cselect_b32 s50, s78, s50
	s_cselect_b32 s85, s35, s81
	s_cselect_b32 s84, s47, s80
	s_cselect_b32 s87, s37, s86
	s_cselect_b32 s86, s43, s83
	v_lshl_add_u64 v[212:213], v[140:141], 0, s[48:49]
	s_mov_b64 s[88:89], 0xc000
	v_lshl_add_u64 v[214:215], v[212:213], 0, s[88:89]
	s_add_i32 m0, s57, 0xc000
	s_mov_b64 s[88:89], 0xe000
	ds_read_b128 v[174:177], v190
	ds_read_b128 v[178:181], v190 offset:1024
	ds_read_b128 v[182:185], v190 offset:2048
	ds_read_b128 v[192:195], v190 offset:3072
	ds_read_b128 v[196:199], v190 offset:4096
	ds_read_b128 v[200:203], v190 offset:5120
	ds_read_b128 v[204:207], v190 offset:6144
	ds_read_b128 v[208:211], v190 offset:7168
	global_load_lds_dwordx4 v[214:215], off
	v_lshl_add_u64 v[212:213], v[212:213], 0, s[88:89]
	s_add_i32 m0, s57, 0xe000
	s_nop 0
	global_load_lds_dwordx4 v[212:213], off
	s_waitcnt vmcnt(8)
	s_waitcnt lgkmcnt(0)
	s_barrier
	s_setprio 1
	s_waitcnt lgkmcnt(0)
	v_mfma_f32_16x16x32_bf16 v[124:127], v[142:145], v[174:177], v[124:127]
	v_mfma_f32_16x16x32_bf16 v[120:123], v[150:153], v[174:177], v[120:123]
	v_mfma_f32_16x16x32_bf16 v[120:123], v[154:157], v[178:181], v[120:123]
	v_mfma_f32_16x16x32_bf16 v[124:127], v[146:149], v[178:181], v[124:127]
	v_mfma_f32_16x16x32_bf16 v[116:119], v[142:145], v[182:185], v[116:119]
	v_mfma_f32_16x16x32_bf16 v[112:115], v[150:153], v[182:185], v[112:115]
	v_mfma_f32_16x16x32_bf16 v[112:115], v[154:157], v[192:195], v[112:115]
	v_mfma_f32_16x16x32_bf16 v[116:119], v[146:149], v[192:195], v[116:119]
	v_mfma_f32_16x16x32_bf16 v[108:111], v[142:145], v[196:199], v[108:111]
	v_mfma_f32_16x16x32_bf16 v[104:107], v[150:153], v[196:199], v[104:107]
	v_mfma_f32_16x16x32_bf16 v[104:107], v[154:157], v[200:203], v[104:107]
	v_mfma_f32_16x16x32_bf16 v[108:111], v[146:149], v[200:203], v[108:111]
	v_mfma_f32_16x16x32_bf16 v[100:103], v[142:145], v[204:207], v[100:103]
	v_mfma_f32_16x16x32_bf16 v[96:99], v[150:153], v[204:207], v[96:99]
	v_mfma_f32_16x16x32_bf16 v[96:99], v[154:157], v[208:211], v[96:99]
	v_mfma_f32_16x16x32_bf16 v[100:103], v[146:149], v[208:211], v[100:103]
	s_setprio 0
	s_setprio 1
	v_mfma_f32_16x16x32_bf16 v[60:63], v[158:161], v[174:177], v[60:63]
	v_mfma_f32_16x16x32_bf16 v[56:59], v[166:169], v[174:177], v[56:59]
	v_mfma_f32_16x16x32_bf16 v[56:59], v[170:173], v[178:181], v[56:59]
	v_mfma_f32_16x16x32_bf16 v[60:63], v[162:165], v[178:181], v[60:63]
	v_mfma_f32_16x16x32_bf16 v[52:55], v[158:161], v[182:185], v[52:55]
	v_mfma_f32_16x16x32_bf16 v[48:51], v[166:169], v[182:185], v[48:51]
	v_mfma_f32_16x16x32_bf16 v[48:51], v[170:173], v[192:195], v[48:51]
	v_mfma_f32_16x16x32_bf16 v[52:55], v[162:165], v[192:195], v[52:55]
	v_mfma_f32_16x16x32_bf16 v[44:47], v[158:161], v[196:199], v[44:47]
	v_mfma_f32_16x16x32_bf16 v[40:43], v[166:169], v[196:199], v[40:43]
	v_mfma_f32_16x16x32_bf16 v[40:43], v[170:173], v[200:203], v[40:43]
	v_mfma_f32_16x16x32_bf16 v[44:47], v[162:165], v[200:203], v[44:47]
	v_mfma_f32_16x16x32_bf16 v[36:39], v[158:161], v[204:207], v[36:39]
	v_mfma_f32_16x16x32_bf16 v[32:35], v[166:169], v[204:207], v[32:35]
	v_mfma_f32_16x16x32_bf16 v[32:35], v[170:173], v[208:211], v[32:35]
	v_mfma_f32_16x16x32_bf16 v[36:39], v[162:165], v[208:211], v[36:39]
	s_setprio 0
	s_barrier
	s_add_i32 s83, s94, s56
	v_lshl_add_u64 v[212:213], s[84:85], 0, v[130:131]
	s_mov_b32 m0, s83
	ds_read_b128 v[174:177], v190 offset:16384
	ds_read_b128 v[178:181], v190 offset:17408
	ds_read_b128 v[182:185], v190 offset:18432
	ds_read_b128 v[192:195], v190 offset:19456
	ds_read_b128 v[196:199], v190 offset:20480
	ds_read_b128 v[200:203], v190 offset:21504
	ds_read_b128 v[204:207], v190 offset:22528
	ds_read_b128 v[208:211], v190 offset:23552
	global_load_lds_dwordx4 v[212:213], off
	v_lshl_add_u64 v[214:215], v[212:213], 0, s[4:5]
	s_add_i32 m0, s83, 0x2000
	s_add_i32 s83, s95, s56
	global_load_lds_dwordx4 v[214:215], off
	v_lshl_add_u64 v[214:215], v[212:213], 0, s[6:7]
	s_mov_b32 m0, s83
	s_nop 0
	global_load_lds_dwordx4 v[214:215], off
	v_lshl_add_u64 v[214:215], v[212:213], 0, s[8:9]
	s_add_i32 m0, s83, 0x2000
	s_nop 0
	global_load_lds_dwordx4 v[214:215], off
	v_lshl_add_u64 v[214:215], s[86:87], 0, v[128:129]
	s_mov_b32 m0, s57
	v_lshl_add_u64 v[216:217], v[214:215], 0, s[10:11]
	global_load_lds_dwordx4 v[214:215], off
	s_mov_b32 m0, s58
	s_nop 0
	global_load_lds_dwordx4 v[216:217], off
	s_waitcnt vmcnt(8)
	s_waitcnt lgkmcnt(0)
	s_barrier
; #define PG8_STAGE(bufoff, gbase, voff) do { _Pragma("unroll") for (int _i = 0; _i < 2; ++_i) \
;         __builtin_amdgcn_global_load_lds((const unsigned*)((const char*)(gbase) + (size_t)_i * p##voff + (voff)), (LAS unsigned*)(lds + (bufoff) + ldsw + _i * 8192), 16, 0, 0); } while (0)
; #define PG8_LDA(dst, b, h) do { _Pragma("unroll") for (int m = 0; m < 4; ++m) _Pragma("unroll") for (int k = 0; k < 2; ++k) dst[m][k] = *(const LAS bf16x8*)(lds + PG8_SA(b, h) + aoff + m * 2048 + k * 1024); } while (0)
; #define PG8_LDB(dst, b, h) do { _Pragma("unroll") for (int n = 0; n < 2; ++n) _Pragma("unroll") for (int k = 0; k < 2; ++k) dst[n][k] = *(const LAS bf16x8*)(lds + PG8_SB(b, h) + boff + n * 2048 + k * 1024); } while (0)
; #define PG8_WAIT_V(n) asm volatile("s_waitcnt vmcnt(" #n ")" ::: "memory")
; #define PG8_WAIT_L(n) asm volatile("s_waitcnt lgkmcnt(" #n ")" ::: "memory")
; #define PG8_BAR __builtin_amdgcn_s_barrier()
; #define PG8_SCHED __builtin_amdgcn_sched_barrier(0)
;     ...
;             PG8_WAIT_V(8); PG8_WAIT_L(0); PG8_BAR; PG8_MMA(1, 0, At, B0); PG8_MMA(1, 1, At, B1); PG8_BAR; PG8_SCHED;
;             PG8_LDB(B0, 1, 0); PG8_LDB(B1, 1, 1); PG8_SCHED; PG8_LDA(At, 1, 0); PG8_STAGE(PG8_SA(0, 1), a2 + hstepA, voffA);
;             PG8_WAIT_V(8); PG8_WAIT_L(0); PG8_BAR; PG8_MMA(0, 0, At, B0); PG8_MMA(0, 1, At, B1); PG8_BAR; PG8_SCHED;
	s_setprio 1
	s_waitcnt lgkmcnt(0)
	v_mfma_f32_16x16x32_bf16 v[92:95], v[142:145], v[174:177], v[92:95]
	v_mfma_f32_16x16x32_bf16 v[88:91], v[150:153], v[174:177], v[88:91]
	v_mfma_f32_16x16x32_bf16 v[88:91], v[154:157], v[178:181], v[88:91]
	v_mfma_f32_16x16x32_bf16 v[92:95], v[146:149], v[178:181], v[92:95]
	v_mfma_f32_16x16x32_bf16 v[84:87], v[142:145], v[182:185], v[84:87]
	v_mfma_f32_16x16x32_bf16 v[80:83], v[150:153], v[182:185], v[80:83]
	v_mfma_f32_16x16x32_bf16 v[80:83], v[154:157], v[192:195], v[80:83]
	v_mfma_f32_16x16x32_bf16 v[84:87], v[146:149], v[192:195], v[84:87]
	v_mfma_f32_16x16x32_bf16 v[76:79], v[142:145], v[196:199], v[76:79]
	v_mfma_f32_16x16x32_bf16 v[72:75], v[150:153], v[196:199], v[72:75]
	v_mfma_f32_16x16x32_bf16 v[72:75], v[154:157], v[200:203], v[72:75]
	v_mfma_f32_16x16x32_bf16 v[76:79], v[146:149], v[200:203], v[76:79]
	v_mfma_f32_16x16x32_bf16 v[68:71], v[142:145], v[204:207], v[68:71]
	v_mfma_f32_16x16x32_bf16 v[64:67], v[150:153], v[204:207], v[64:67]
	v_mfma_f32_16x16x32_bf16 v[64:67], v[154:157], v[208:211], v[64:67]
	v_mfma_f32_16x16x32_bf16 v[68:71], v[146:149], v[208:211], v[68:71]
	s_setprio 0
	s_setprio 1
	v_mfma_f32_16x16x32_bf16 v[28:31], v[158:161], v[174:177], v[28:31]
	v_mfma_f32_16x16x32_bf16 v[24:27], v[166:169], v[174:177], v[24:27]
	v_mfma_f32_16x16x32_bf16 v[24:27], v[170:173], v[178:181], v[24:27]
	v_mfma_f32_16x16x32_bf16 v[28:31], v[162:165], v[178:181], v[28:31]
	v_mfma_f32_16x16x32_bf16 v[20:23], v[158:161], v[182:185], v[20:23]
	v_mfma_f32_16x16x32_bf16 v[16:19], v[166:169], v[182:185], v[16:19]
	v_mfma_f32_16x16x32_bf16 v[16:19], v[170:173], v[192:195], v[16:19]
	v_mfma_f32_16x16x32_bf16 v[20:23], v[162:165], v[192:195], v[20:23]
	v_mfma_f32_16x16x32_bf16 v[12:15], v[158:161], v[196:199], v[12:15]
	v_mfma_f32_16x16x32_bf16 v[8:11], v[166:169], v[196:199], v[8:11]
	v_mfma_f32_16x16x32_bf16 v[8:11], v[170:173], v[200:203], v[8:11]
	v_mfma_f32_16x16x32_bf16 v[12:15], v[162:165], v[200:203], v[12:15]
	v_mfma_f32_16x16x32_bf16 v[4:7], v[158:161], v[204:207], v[4:7]
	v_mfma_f32_16x16x32_bf16 v[0:3], v[166:169], v[204:207], v[0:3]
	v_mfma_f32_16x16x32_bf16 v[0:3], v[170:173], v[208:211], v[0:3]
	v_mfma_f32_16x16x32_bf16 v[4:7], v[162:165], v[208:211], v[4:7]
	s_setprio 0
	s_barrier
	s_add_i32 s83, 0, 0x18000
	v_add_u32_e32 v132, s83, v187
	s_add_i32 s84, 0, 0x1c000
	ds_read_b128 v[142:145], v132
	ds_read_b128 v[146:149], v132 offset:1024
	ds_read_b128 v[150:153], v132 offset:2048
	ds_read_b128 v[154:157], v132 offset:3072
	v_add_u32_e32 v132, s84, v187
	ds_read_b128 v[158:161], v132
	ds_read_b128 v[162:165], v132 offset:1024
	ds_read_b128 v[166:169], v132 offset:2048
	ds_read_b128 v[170:173], v132 offset:3072
	s_mov_b32 m0, s59
	v_lshl_add_u64 v[216:217], v[214:215], 0, s[12:13]
	ds_read_b128 v[174:177], v190 offset:32768
	ds_read_b128 v[178:181], v190 offset:33792
	ds_read_b128 v[182:185], v190 offset:34816
	ds_read_b128 v[192:195], v190 offset:35840
	ds_read_b128 v[196:199], v190 offset:36864
	ds_read_b128 v[200:203], v190 offset:37888
	ds_read_b128 v[204:207], v190 offset:38912
	ds_read_b128 v[208:211], v190 offset:39936
	global_load_lds_dwordx4 v[216:217], off
	v_lshl_add_u64 v[214:215], v[214:215], 0, s[14:15]
	s_mov_b32 m0, s60
	s_nop 0
	global_load_lds_dwordx4 v[214:215], off
	s_waitcnt vmcnt(8)
	s_waitcnt lgkmcnt(0)
	s_barrier
	s_setprio 1
	s_waitcnt lgkmcnt(0)
	v_mfma_f32_16x16x32_bf16 v[124:127], v[142:145], v[174:177], v[124:127]
	v_mfma_f32_16x16x32_bf16 v[120:123], v[150:153], v[174:177], v[120:123]
	v_mfma_f32_16x16x32_bf16 v[120:123], v[154:157], v[178:181], v[120:123]
	v_mfma_f32_16x16x32_bf16 v[124:127], v[146:149], v[178:181], v[124:127]
	v_mfma_f32_16x16x32_bf16 v[116:119], v[142:145], v[182:185], v[116:119]
	v_mfma_f32_16x16x32_bf16 v[112:115], v[150:153], v[182:185], v[112:115]
	v_mfma_f32_16x16x32_bf16 v[112:115], v[154:157], v[192:195], v[112:115]
	v_mfma_f32_16x16x32_bf16 v[116:119], v[146:149], v[192:195], v[116:119]
	v_mfma_f32_16x16x32_bf16 v[108:111], v[142:145], v[196:199], v[108:111]
	v_mfma_f32_16x16x32_bf16 v[104:107], v[150:153], v[196:199], v[104:107]
	v_mfma_f32_16x16x32_bf16 v[104:107], v[154:157], v[200:203], v[104:107]
	v_mfma_f32_16x16x32_bf16 v[108:111], v[146:149], v[200:203], v[108:111]
	v_mfma_f32_16x16x32_bf16 v[100:103], v[142:145], v[204:207], v[100:103]
	v_mfma_f32_16x16x32_bf16 v[96:99], v[150:153], v[204:207], v[96:99]
	v_mfma_f32_16x16x32_bf16 v[96:99], v[154:157], v[208:211], v[96:99]
	v_mfma_f32_16x16x32_bf16 v[100:103], v[146:149], v[208:211], v[100:103]
	s_setprio 0
	s_setprio 1
	v_mfma_f32_16x16x32_bf16 v[60:63], v[158:161], v[174:177], v[60:63]
	v_mfma_f32_16x16x32_bf16 v[56:59], v[166:169], v[174:177], v[56:59]
	v_mfma_f32_16x16x32_bf16 v[56:59], v[170:173], v[178:181], v[56:59]
	v_mfma_f32_16x16x32_bf16 v[60:63], v[162:165], v[178:181], v[60:63]
	v_mfma_f32_16x16x32_bf16 v[52:55], v[158:161], v[182:185], v[52:55]
	v_mfma_f32_16x16x32_bf16 v[48:51], v[166:169], v[182:185], v[48:51]
	v_mfma_f32_16x16x32_bf16 v[48:51], v[170:173], v[192:195], v[48:51]
	v_mfma_f32_16x16x32_bf16 v[52:55], v[162:165], v[192:195], v[52:55]
	v_mfma_f32_16x16x32_bf16 v[44:47], v[158:161], v[196:199], v[44:47]
	v_mfma_f32_16x16x32_bf16 v[40:43], v[166:169], v[196:199], v[40:43]
	v_mfma_f32_16x16x32_bf16 v[40:43], v[170:173], v[200:203], v[40:43]
	v_mfma_f32_16x16x32_bf16 v[44:47], v[162:165], v[200:203], v[44:47]
	v_mfma_f32_16x16x32_bf16 v[36:39], v[158:161], v[204:207], v[36:39]
	v_mfma_f32_16x16x32_bf16 v[32:35], v[166:169], v[204:207], v[32:35]
	v_mfma_f32_16x16x32_bf16 v[32:35], v[170:173], v[208:211], v[32:35]
	v_mfma_f32_16x16x32_bf16 v[36:39], v[162:165], v[208:211], v[36:39]
	s_setprio 0
	s_barrier
; #define PG8_STAGE(bufoff, gbase, voff) do { _Pragma("unroll") for (int _i = 0; _i < 2; ++_i) \
;         __builtin_amdgcn_global_load_lds((const unsigned*)((const char*)(gbase) + (size_t)_i * p##voff + (voff)), (LAS unsigned*)(lds + (bufoff) + ldsw + _i * 8192), 16, 0, 0); } while (0)
; #define PG8_LDA(dst, b, h) do { _Pragma("unroll") for (int m = 0; m < 4; ++m) _Pragma("unroll") for (int k = 0; k < 2; ++k) dst[m][k] = *(const LAS bf16x8*)(lds + PG8_SA(b, h) + aoff + m * 2048 + k * 1024); } while (0)
; #define PG8_WAIT_V(n) asm volatile("s_waitcnt vmcnt(" #n ")" ::: "memory")
; #define PG8_WAIT_L(n) asm volatile("s_waitcnt lgkmcnt(" #n ")" ::: "memory")
; #define PG8_BAR __builtin_amdgcn_s_barrier()
; #define PG8_SCHED __builtin_amdgcn_sched_barrier(0)
;     ...
;             PG8_LDA(At, 1, 1); PG8_STAGE(PG8_SB(1, 0), b3, voffB); PG8_STAGE(PG8_SB(1, 1), b3 + hstepB, voffB); PG8_STAGE(PG8_SA(1, 0), a3, voffA);
;             PG8_WAIT_V(8); PG8_WAIT_L(0); PG8_BAR; PG8_MMA(1, 0, At, B0); PG8_MMA(1, 1, At, B1); PG8_BAR; PG8_SCHED;
;     __device__ __forceinline__ void operator()(const Acc& acc, const Unit& u, int wr, int wc, int fr, int fq) const {
;     ...
;         const int rowb = u.pm * 256 + wr * 64 + fr, col0 = u.pn * 256 + wc * 32 + 8 * fq; const int b = (u.pm * 256) / S;
;         const size_t yb = (((size_t)u.pm * 16 + u.pn) * 256 + (wr * 64 + fr)) * 256 + wc * 32 + 8 * fq;
; #pragma unroll
;         for (int bj = 0; bj < 2; ++bj) {
;             f32x4 gm[2], G[2], Bc[2];
; #pragma unroll
;             for (int n = 0; n < 2; ++n) { const int c = col0 + bj * 128 + n * 4; gm[n] = *(const f32x4*)(gate + (size_t)b * NADA + c) + 1.0f; G[n] = *(const f32x4*)(lg + c) * ALPHA; Bc[n] = *(const f32x4*)(lb + c) * ALPHA; }
; #pragma unroll
;             for (int hf = 0; hf < 2; ++hf) {
;                 u32x4 yv[4]; f32x2 st[4];
; #pragma unroll
;                 for (int m = 0; m < 4; ++m) { const int row = rowb + hf * 128 + m * 16; yv[m] = *(const u32x4*)(y1 + yb + (size_t)(hf * 128 + m * 16) * 256 + bj * 128); st[m] = *(const f32x2*)(stats + (size_t)row * 2); }
	s_add_i32 s83, s83, s56
	v_lshl_add_u64 v[214:215], v[212:213], 0, s[20:21]
	s_mov_b32 m0, s83
	ds_read_b128 v[174:177], v190 offset:49152
	ds_read_b128 v[178:181], v190 offset:50176
	ds_read_b128 v[182:185], v190 offset:51200
	ds_read_b128 v[192:195], v190 offset:52224
	ds_read_b128 v[196:199], v190 offset:53248
	ds_read_b128 v[200:203], v190 offset:54272
	ds_read_b128 v[204:207], v190 offset:55296
	ds_read_b128 v[208:211], v190 offset:56320
	global_load_lds_dwordx4 v[214:215], off
	v_lshl_add_u64 v[214:215], v[212:213], 0, s[22:23]
	s_add_i32 m0, s83, 0x2000
	s_add_i32 s83, s84, s56
	global_load_lds_dwordx4 v[214:215], off
	v_lshl_add_u64 v[214:215], v[212:213], 0, s[24:25]
	s_mov_b32 m0, s83
	v_lshl_add_u64 v[212:213], v[212:213], 0, s[26:27]
	global_load_lds_dwordx4 v[214:215], off
	s_add_i32 m0, s83, 0x2000
	s_nop 0
	global_load_lds_dwordx4 v[212:213], off
	v_lshl_add_u64 v[212:213], s[50:51], 0, v[128:129]
	s_mov_b32 m0, s71
	s_nop 0
	global_load_lds_dwordx4 v[212:213], off
	v_lshl_add_u64 v[212:213], v[212:213], 0, s[10:11]
	s_mov_b32 m0, s72
	s_nop 0
	global_load_lds_dwordx4 v[212:213], off
	s_waitcnt vmcnt(8)
	s_waitcnt lgkmcnt(0)
	s_barrier
	s_setprio 1
	s_waitcnt lgkmcnt(0)
	v_mfma_f32_16x16x32_bf16 v[92:95], v[142:145], v[174:177], v[92:95]
	v_mfma_f32_16x16x32_bf16 v[88:91], v[150:153], v[174:177], v[88:91]
	v_mfma_f32_16x16x32_bf16 v[88:91], v[154:157], v[178:181], v[88:91]
	v_mfma_f32_16x16x32_bf16 v[92:95], v[146:149], v[178:181], v[92:95]
	v_mfma_f32_16x16x32_bf16 v[84:87], v[142:145], v[182:185], v[84:87]
	v_mfma_f32_16x16x32_bf16 v[80:83], v[150:153], v[182:185], v[80:83]
	v_mfma_f32_16x16x32_bf16 v[80:83], v[154:157], v[192:195], v[80:83]
	v_mfma_f32_16x16x32_bf16 v[84:87], v[146:149], v[192:195], v[84:87]
	v_mfma_f32_16x16x32_bf16 v[76:79], v[142:145], v[196:199], v[76:79]
	v_mfma_f32_16x16x32_bf16 v[72:75], v[150:153], v[196:199], v[72:75]
	v_mfma_f32_16x16x32_bf16 v[72:75], v[154:157], v[200:203], v[72:75]
	v_mfma_f32_16x16x32_bf16 v[76:79], v[146:149], v[200:203], v[76:79]
	v_mfma_f32_16x16x32_bf16 v[68:71], v[142:145], v[204:207], v[68:71]
	v_mfma_f32_16x16x32_bf16 v[64:67], v[150:153], v[204:207], v[64:67]
	v_mfma_f32_16x16x32_bf16 v[64:67], v[154:157], v[208:211], v[64:67]
	v_mfma_f32_16x16x32_bf16 v[68:71], v[146:149], v[208:211], v[68:71]
	s_setprio 0
	s_setprio 1
	v_mfma_f32_16x16x32_bf16 v[28:31], v[158:161], v[174:177], v[28:31]
	v_mfma_f32_16x16x32_bf16 v[24:27], v[166:169], v[174:177], v[24:27]
	v_mfma_f32_16x16x32_bf16 v[24:27], v[170:173], v[178:181], v[24:27]
	v_mfma_f32_16x16x32_bf16 v[28:31], v[162:165], v[178:181], v[28:31]
	v_mfma_f32_16x16x32_bf16 v[20:23], v[158:161], v[182:185], v[20:23]
	v_mfma_f32_16x16x32_bf16 v[16:19], v[166:169], v[182:185], v[16:19]
	v_mfma_f32_16x16x32_bf16 v[16:19], v[170:173], v[192:195], v[16:19]
	v_mfma_f32_16x16x32_bf16 v[20:23], v[162:165], v[192:195], v[20:23]
	v_mfma_f32_16x16x32_bf16 v[12:15], v[158:161], v[196:199], v[12:15]
	v_mfma_f32_16x16x32_bf16 v[8:11], v[166:169], v[196:199], v[8:11]
	v_mfma_f32_16x16x32_bf16 v[8:11], v[170:173], v[200:203], v[8:11]
	v_mfma_f32_16x16x32_bf16 v[12:15], v[162:165], v[200:203], v[12:15]
	v_mfma_f32_16x16x32_bf16 v[4:7], v[158:161], v[204:207], v[4:7]
	v_mfma_f32_16x16x32_bf16 v[0:3], v[166:169], v[204:207], v[0:3]
	v_mfma_f32_16x16x32_bf16 v[0:3], v[170:173], v[208:211], v[0:3]
	v_mfma_f32_16x16x32_bf16 v[4:7], v[162:165], v[208:211], v[4:7]
	s_setprio 0
	s_barrier
	s_add_i32 s82, s82, 2
	s_add_u32 s80, s80, 0x100
	s_addc_u32 s81, s81, 0
	s_add_u32 s48, s48, 0x10000
	s_addc_u32 s49, s49, 0
	s_cmpk_gt_u32 s82, 0xfd
	s_cbranch_scc0 .LBB0_1281
	s_lshl_b32 s37, s46, 8
	v_lshrrev_b32_e32 v132, 1, v191
	s_or_b32 s37, s37, s74
	v_and_b32_e32 v141, 56, v132
	s_ashr_i32 s43, s42, 31
	v_add_u32_e32 v140, s37, v141
	s_lshr_b32 s37, s43, 28
	s_lshl_b32 s35, s42, 8
	s_add_i32 s37, s42, s37
	s_ashr_i32 s47, s46, 31
	s_add_i32 s35, s35, s73
	s_ashr_i32 s37, s37, 4
	s_lshl_b64 s[42:43], s[42:43], 12
	s_lshl_b64 s[44:45], s[46:47], 8
	v_and_b32_e32 v150, 15, v191
	s_add_u32 s42, s42, s44
	s_addc_u32 s43, s43, s45
	v_or_b32_e32 v132, s73, v150
	v_lshl_add_u64 v[148:149], s[42:43], 0, v[132:133]
	s_mul_hi_i32 s43, s37, 0x18000
	s_mul_i32 s37, s37, 0x18000
	v_add_u32_e32 v132, s74, v141
	v_ashrrev_i32_e32 v141, 31, v140
	v_readlane_b32 s76, v245, 10
	s_add_u32 s42, s69, s37
	v_lshlrev_b64 v[220:221], 9, v[148:149]
	v_or_b32_e32 v154, s35, v150
	v_lshlrev_b64 v[140:141], 2, v[140:141]
	v_readlane_b32 s78, v245, 12
	v_readlane_b32 s79, v245, 13
	v_readlane_b32 s80, v245, 14
	v_readlane_b32 s81, v245, 15
	s_addc_u32 s43, s70, s43
	v_lshl_or_b32 v220, v132, 1, v220
	v_ashrrev_i32_e32 v155, 31, v154
	v_lshl_add_u64 v[142:143], s[78:79], 0, v[140:141]
	v_lshl_add_u64 v[144:145], s[80:81], 0, v[140:141]
	v_lshl_add_u64 v[146:147], s[42:43], 0, v[140:141]
	v_lshl_add_u64 v[148:149], s[16:17], 0, v[220:221]
	v_lshl_add_u64 v[140:141], v[154:155], 3, s[18:19]
	global_load_dwordx4 v[164:167], v[142:143], off offset:16
	global_load_dwordx4 v[168:171], v[142:143], off
	global_load_dwordx4 v[182:185], v[144:145], off offset:16
	global_load_dwordx4 v[192:195], v[144:145], off
	global_load_dwordx4 v[196:199], v[146:147], off offset:16
	global_load_dwordx4 v[200:203], v[146:147], off
	global_load_dwordx4 v[204:207], v[148:149], off
	global_load_dwordx2 v[222:223], v[140:141], off
	v_or_b32_e32 v152, 16, v154
	v_add_co_u32_e32 v150, vcc, s66, v148
	v_ashrrev_i32_e32 v153, 31, v152
	s_nop 0
	v_addc_co_u32_e32 v151, vcc, 0, v149, vcc
	v_lshl_add_u64 v[152:153], v[152:153], 3, s[18:19]
	global_load_dwordx4 v[208:211], v[150:151], off
	global_load_dwordx2 v[224:225], v[152:153], off
	v_add_co_u32_e32 v158, vcc, s67, v148
	v_or_b32_e32 v156, 32, v154
	s_nop 0
	v_addc_co_u32_e32 v159, vcc, 0, v149, vcc
	v_or_b32_e32 v154, 48, v154
	v_ashrrev_i32_e32 v157, 31, v156
	global_load_dwordx4 v[212:215], v[158:159], off
	v_ashrrev_i32_e32 v155, 31, v154
	v_lshl_add_u64 v[160:161], v[156:157], 3, s[18:19]
	v_add_co_u32_e32 v156, vcc, s68, v148
	v_lshl_add_u64 v[154:155], v[154:155], 3, s[18:19]
	s_nop 0
	v_addc_co_u32_e32 v157, vcc, 0, v149, vcc
	global_load_dwordx2 v[226:227], v[160:161], off
	global_load_dwordx4 v[216:219], v[156:157], off
	global_load_dwordx2 v[228:229], v[154:155], off
	v_readlane_b32 s42, v245, 61
	v_readlane_b32 s43, v245, 62
	s_mov_b32 s46, s34
	s_mov_b64 s[48:49], s[40:41]
	s_mov_b64 s[44:45], s[38:39]
	v_readlane_b32 s77, v245, 11
	v_readlane_b32 s82, v245, 16
	v_readlane_b32 s83, v245, 17
	v_readlane_b32 s84, v245, 18
	v_readlane_b32 s85, v245, 19
	v_readlane_b32 s86, v245, 20
	v_readlane_b32 s87, v245, 21
	v_readlane_b32 s88, v245, 22
	v_readlane_b32 s89, v245, 23
	v_readlane_b32 s90, v245, 24
	v_readlane_b32 s91, v245, 25
	s_waitcnt vmcnt(0)
; __device__ __forceinline__ u32x4 pack8f(f32x4 lo, f32x4 hi) { u32x4 w; w.x = cvtpk(lo[0], lo[1]); w.y = cvtpk(lo[2], lo[3]); w.z = cvtpk(hi[0], hi[1]); w.w = cvtpk(hi[2], hi[3]); return w; }
;     __device__ __forceinline__ void operator()(const Acc& acc, const Unit& u, int wr, int wc, int fr, int fq) const {
;     ...
;         for (int bj = 0; bj < 2; ++bj) {
;             f32x4 gm[2], G[2], Bc[2];
; #pragma unroll
;             for (int n = 0; n < 2; ++n) { const int c = col0 + bj * 128 + n * 4; gm[n] = *(const f32x4*)(gate + (size_t)b * NADA + c) + 1.0f; G[n] = *(const f32x4*)(lg + c) * ALPHA; Bc[n] = *(const f32x4*)(lb + c) * ALPHA; }
; #pragma unroll
;             for (int hf = 0; hf < 2; ++hf) {
;                 u32x4 yv[4]; f32x2 st[4];
; #pragma unroll
;                 for (int m = 0; m < 4; ++m) { const int row = rowb + hf * 128 + m * 16; yv[m] = *(const u32x4*)(y1 + yb + (size_t)(hf * 128 + m * 16) * 256 + bj * 128); st[m] = *(const f32x2*)(stats + (size_t)row * 2); }
; #pragma unroll
;                 for (int m = 0; m < 4; ++m) { const int row = rowb + hf * 128 + m * 16;
;                     f32x4 lo, hi; unpack8(yv[m], lo, hi); const float r = st[m][1], mr = st[m][0] * r;
;                     lo = (lo * r - mr) * G[0] + Bc[0] + gm[0] * acc[hf][bj][m][0]; hi = (hi * r - mr) * G[1] + Bc[1] + gm[1] * acc[hf][bj][m][1];
;                     *(u32x4*)(y2 + yb + (size_t)(hf * 128 + m * 16) * 256 + bj * 128) = pack8f(lo, hi); }
	v_pk_mul_f32 v[162:163], v[166:167], s[28:29] op_sel_hi:[1,0]
	v_pk_mul_f32 v[166:167], v[184:185], s[28:29] op_sel_hi:[1,0]
	v_pk_mul_f32 v[178:179], v[194:195], s[28:29] op_sel_hi:[1,0]
	v_pk_mul_f32 v[180:181], v[192:193], s[28:29] op_sel_hi:[1,0]
	v_pk_add_f32 v[184:185], v[200:201], 1.0 op_sel_hi:[1,0]
	v_lshlrev_b32_e32 v192, 16, v204
	v_and_b32_e32 v193, 0xffff0000, v204
	v_lshlrev_b32_e32 v194, 16, v205
	v_and_b32_e32 v195, 0xffff0000, v205
	v_pk_mul_f32 v[200:201], v[222:223], v[222:223] op_sel:[0,1] op_sel_hi:[1,0]
	v_pk_mul_f32 v[174:175], v[170:171], s[28:29] op_sel_hi:[1,0]
	v_pk_mul_f32 v[176:177], v[168:169], s[28:29] op_sel_hi:[1,0]
	v_pk_fma_f32 v[192:193], v[222:223], v[192:193], v[200:201] op_sel:[1,0,0] op_sel_hi:[1,1,0] neg_lo:[0,0,1] neg_hi:[0,0,1]
	v_pk_fma_f32 v[194:195], v[222:223], v[194:195], v[200:201] op_sel:[1,0,0] op_sel_hi:[1,1,0] neg_lo:[0,0,1] neg_hi:[0,0,1]
	v_pk_mul_f32 v[172:173], v[182:183], s[28:29] op_sel_hi:[1,0]
	v_pk_add_f32 v[182:183], v[202:203], 1.0 op_sel_hi:[1,0]
	v_pk_add_f32 v[168:169], v[198:199], 1.0 op_sel_hi:[1,0]
	v_pk_add_f32 v[170:171], v[196:197], 1.0 op_sel_hi:[1,0]
	v_lshlrev_b32_e32 v196, 16, v206
	v_and_b32_e32 v197, 0xffff0000, v206
	v_lshlrev_b32_e32 v198, 16, v207
	v_and_b32_e32 v199, 0xffff0000, v207
	v_pk_fma_f32 v[194:195], v[174:175], v[194:195], v[178:179]
	v_pk_fma_f32 v[192:193], v[176:177], v[192:193], v[180:181]
	v_pk_mul_f32 v[164:165], v[164:165], s[28:29] op_sel_hi:[1,0]
	v_pk_fma_f32 v[126:127], v[126:127], v[182:183], v[194:195]
	v_pk_fma_f32 v[124:125], v[124:125], v[184:185], v[192:193]
	v_pk_fma_f32 v[192:193], v[222:223], v[196:197], v[200:201] op_sel:[1,0,0] op_sel_hi:[1,1,0] neg_lo:[0,0,1] neg_hi:[0,0,1]
	v_pk_fma_f32 v[194:195], v[222:223], v[198:199], v[200:201] op_sel:[1,0,0] op_sel_hi:[1,1,0] neg_lo:[0,0,1] neg_hi:[0,0,1]
	v_pk_fma_f32 v[192:193], v[164:165], v[192:193], v[172:173]
	v_pk_fma_f32 v[194:195], v[162:163], v[194:195], v[166:167]
	v_pk_fma_f32 v[120:121], v[120:121], v[170:171], v[192:193]
	v_pk_fma_f32 v[194:195], v[122:123], v[168:169], v[194:195]
	v_cvt_pk_bf16_f32 v122, v124, v125
	v_cvt_pk_bf16_f32 v123, v126, v127
	v_cvt_pk_bf16_f32 v124, v120, v121
	v_cvt_pk_bf16_f32 v125, v194, v195
	v_lshl_add_u64 v[120:121], s[42:43], 0, v[220:221]
	global_store_dwordx4 v[120:121], v[122:125], off
	v_pk_mul_f32 v[194:195], v[224:225], v[224:225] op_sel:[0,1] op_sel_hi:[1,0]
	v_lshlrev_b32_e32 v126, 16, v210
	v_lshlrev_b32_e32 v124, 16, v209
	v_and_b32_e32 v125, 0xffff0000, v209
	v_lshlrev_b32_e32 v122, 16, v208
	v_and_b32_e32 v123, 0xffff0000, v208
	v_pk_fma_f32 v[124:125], v[224:225], v[124:125], v[194:195] op_sel:[1,0,0] op_sel_hi:[1,1,0] neg_lo:[0,0,1] neg_hi:[0,0,1]
	v_and_b32_e32 v127, 0xffff0000, v210
	v_pk_fma_f32 v[122:123], v[224:225], v[122:123], v[194:195] op_sel:[1,0,0] op_sel_hi:[1,1,0] neg_lo:[0,0,1] neg_hi:[0,0,1]
	v_pk_fma_f32 v[124:125], v[174:175], v[124:125], v[178:179]
	v_lshlrev_b32_e32 v192, 16, v211
	v_and_b32_e32 v193, 0xffff0000, v211
	v_pk_fma_f32 v[122:123], v[176:177], v[122:123], v[180:181]
	v_pk_fma_f32 v[118:119], v[118:119], v[182:183], v[124:125]
	v_pk_fma_f32 v[124:125], v[224:225], v[126:127], v[194:195] op_sel:[1,0,0] op_sel_hi:[1,1,0] neg_lo:[0,0,1] neg_hi:[0,0,1]
	v_pk_fma_f32 v[116:117], v[116:117], v[184:185], v[122:123]
	v_pk_fma_f32 v[122:123], v[224:225], v[192:193], v[194:195] op_sel:[1,0,0] op_sel_hi:[1,1,0] neg_lo:[0,0,1] neg_hi:[0,0,1]
	v_pk_fma_f32 v[124:125], v[164:165], v[124:125], v[172:173]
	v_pk_fma_f32 v[122:123], v[162:163], v[122:123], v[166:167]
	v_pk_fma_f32 v[112:113], v[112:113], v[170:171], v[124:125]
	v_pk_fma_f32 v[122:123], v[114:115], v[168:169], v[122:123]
	v_cvt_pk_bf16_f32 v114, v116, v117
	v_cvt_pk_bf16_f32 v116, v112, v113
	v_add_co_u32_e32 v112, vcc, s66, v120
	v_cvt_pk_bf16_f32 v115, v118, v119
	v_cvt_pk_bf16_f32 v117, v122, v123
	v_addc_co_u32_e32 v113, vcc, 0, v121, vcc
	global_store_dwordx4 v[112:113], v[114:117], off
	v_pk_mul_f32 v[124:125], v[226:227], v[226:227] op_sel:[0,1] op_sel_hi:[1,0]
	v_lshlrev_b32_e32 v118, 16, v214
	v_lshlrev_b32_e32 v116, 16, v213
	v_and_b32_e32 v117, 0xffff0000, v213
	v_lshlrev_b32_e32 v114, 16, v212
	v_and_b32_e32 v115, 0xffff0000, v212
	v_pk_fma_f32 v[116:117], v[226:227], v[116:117], v[124:125] op_sel:[1,0,0] op_sel_hi:[1,1,0] neg_lo:[0,0,1] neg_hi:[0,0,1]
	v_and_b32_e32 v119, 0xffff0000, v214
	v_pk_fma_f32 v[114:115], v[226:227], v[114:115], v[124:125] op_sel:[1,0,0] op_sel_hi:[1,1,0] neg_lo:[0,0,1] neg_hi:[0,0,1]
	v_pk_fma_f32 v[116:117], v[174:175], v[116:117], v[178:179]
	v_lshlrev_b32_e32 v122, 16, v215
	v_and_b32_e32 v123, 0xffff0000, v215
	v_pk_fma_f32 v[114:115], v[176:177], v[114:115], v[180:181]
	v_pk_fma_f32 v[110:111], v[110:111], v[182:183], v[116:117]
	v_pk_fma_f32 v[116:117], v[226:227], v[118:119], v[124:125] op_sel:[1,0,0] op_sel_hi:[1,1,0] neg_lo:[0,0,1] neg_hi:[0,0,1]
	v_pk_fma_f32 v[108:109], v[108:109], v[184:185], v[114:115]
	v_pk_fma_f32 v[114:115], v[226:227], v[122:123], v[124:125] op_sel:[1,0,0] op_sel_hi:[1,1,0] neg_lo:[0,0,1] neg_hi:[0,0,1]
	v_pk_fma_f32 v[116:117], v[164:165], v[116:117], v[172:173]
	v_pk_fma_f32 v[114:115], v[162:163], v[114:115], v[166:167]
	v_pk_fma_f32 v[104:105], v[104:105], v[170:171], v[116:117]
	v_pk_fma_f32 v[114:115], v[106:107], v[168:169], v[114:115]
	v_cvt_pk_bf16_f32 v106, v108, v109
	v_cvt_pk_bf16_f32 v108, v104, v105
	v_add_co_u32_e32 v104, vcc, s67, v120
	v_cvt_pk_bf16_f32 v107, v110, v111
	v_cvt_pk_bf16_f32 v109, v114, v115
	v_addc_co_u32_e32 v105, vcc, 0, v121, vcc
	global_store_dwordx4 v[104:105], v[106:109], off
	v_pk_mul_f32 v[116:117], v[228:229], v[228:229] op_sel:[0,1] op_sel_hi:[1,0]
; __device__ __forceinline__ u32x4 pack8f(f32x4 lo, f32x4 hi) { u32x4 w; w.x = cvtpk(lo[0], lo[1]); w.y = cvtpk(lo[2], lo[3]); w.z = cvtpk(hi[0], hi[1]); w.w = cvtpk(hi[2], hi[3]); return w; }
;     __device__ __forceinline__ void operator()(const Acc& acc, const Unit& u, int wr, int wc, int fr, int fq) const {
;     ...
;             for (int hf = 0; hf < 2; ++hf) {
;                 u32x4 yv[4]; f32x2 st[4];
; #pragma unroll
;                 for (int m = 0; m < 4; ++m) { const int row = rowb + hf * 128 + m * 16; yv[m] = *(const u32x4*)(y1 + yb + (size_t)(hf * 128 + m * 16) * 256 + bj * 128); st[m] = *(const f32x2*)(stats + (size_t)row * 2); }
; #pragma unroll
;                 for (int m = 0; m < 4; ++m) { const int row = rowb + hf * 128 + m * 16;
;                     f32x4 lo, hi; unpack8(yv[m], lo, hi); const float r = st[m][1], mr = st[m][0] * r;
;                     lo = (lo * r - mr) * G[0] + Bc[0] + gm[0] * acc[hf][bj][m][0]; hi = (hi * r - mr) * G[1] + Bc[1] + gm[1] * acc[hf][bj][m][1];
;                     *(u32x4*)(y2 + yb + (size_t)(hf * 128 + m * 16) * 256 + bj * 128) = pack8f(lo, hi); }
	v_lshlrev_b32_e32 v110, 16, v218
	v_lshlrev_b32_e32 v108, 16, v217
	v_and_b32_e32 v109, 0xffff0000, v217
	v_lshlrev_b32_e32 v106, 16, v216
	v_and_b32_e32 v107, 0xffff0000, v216
	v_pk_fma_f32 v[108:109], v[228:229], v[108:109], v[116:117] op_sel:[1,0,0] op_sel_hi:[1,1,0] neg_lo:[0,0,1] neg_hi:[0,0,1]
	v_and_b32_e32 v111, 0xffff0000, v218
	v_pk_fma_f32 v[106:107], v[228:229], v[106:107], v[116:117] op_sel:[1,0,0] op_sel_hi:[1,1,0] neg_lo:[0,0,1] neg_hi:[0,0,1]
	v_pk_fma_f32 v[108:109], v[174:175], v[108:109], v[178:179]
	v_lshlrev_b32_e32 v114, 16, v219
	v_and_b32_e32 v115, 0xffff0000, v219
	v_pk_fma_f32 v[106:107], v[176:177], v[106:107], v[180:181]
	v_pk_fma_f32 v[102:103], v[102:103], v[182:183], v[108:109]
	v_pk_fma_f32 v[108:109], v[228:229], v[110:111], v[116:117] op_sel:[1,0,0] op_sel_hi:[1,1,0] neg_lo:[0,0,1] neg_hi:[0,0,1]
	v_pk_fma_f32 v[100:101], v[100:101], v[184:185], v[106:107]
	v_pk_fma_f32 v[106:107], v[228:229], v[114:115], v[116:117] op_sel:[1,0,0] op_sel_hi:[1,1,0] neg_lo:[0,0,1] neg_hi:[0,0,1]
	v_pk_fma_f32 v[108:109], v[164:165], v[108:109], v[172:173]
	v_pk_fma_f32 v[106:107], v[162:163], v[106:107], v[166:167]
	v_pk_fma_f32 v[96:97], v[96:97], v[170:171], v[108:109]
	v_pk_fma_f32 v[106:107], v[98:99], v[168:169], v[106:107]
	v_cvt_pk_bf16_f32 v98, v100, v101
	v_cvt_pk_bf16_f32 v100, v96, v97
	v_add_co_u32_e32 v96, vcc, s68, v120
	v_cvt_pk_bf16_f32 v99, v102, v103
	v_cvt_pk_bf16_f32 v101, v106, v107
	v_addc_co_u32_e32 v97, vcc, 0, v121, vcc
	global_store_dwordx4 v[96:97], v[98:101], off
	s_mov_b32 s42, s36
	s_nop 0
	v_add_co_u32_e32 v98, vcc, s62, v148
	s_nop 1
	v_addc_co_u32_e32 v99, vcc, 0, v149, vcc
	global_load_dwordx4 v[108:111], v[98:99], off
	global_load_dwordx2 v[118:119], v[140:141], off offset:1024
	v_add_co_u32_e32 v100, vcc, s63, v148
	s_waitcnt vmcnt(1)
	v_lshlrev_b32_e32 v200, 16, v108
	v_addc_co_u32_e32 v101, vcc, 0, v149, vcc
	global_load_dwordx4 v[114:117], v[100:101], off
	global_load_dwordx2 v[126:127], v[140:141], off offset:1152
	v_add_co_u32_e32 v102, vcc, s64, v148
	v_and_b32_e32 v201, 0xffff0000, v108
	s_nop 0
	v_addc_co_u32_e32 v103, vcc, 0, v149, vcc
	global_load_dwordx4 v[122:125], v[102:103], off
	global_load_dwordx2 v[196:197], v[140:141], off offset:1280
	v_add_co_u32_e32 v106, vcc, s65, v148
	v_lshlrev_b32_e32 v108, 16, v109
	s_nop 0
	v_addc_co_u32_e32 v107, vcc, 0, v149, vcc
	global_load_dwordx4 v[192:195], v[106:107], off
	global_load_dwordx2 v[198:199], v[140:141], off offset:1408
	v_and_b32_e32 v109, 0xffff0000, v109
	s_waitcnt vmcnt(6)
	v_pk_mul_f32 v[204:205], v[118:119], v[118:119] op_sel:[0,1] op_sel_hi:[1,0]
	v_lshlrev_b32_e32 v202, 16, v110
	v_pk_fma_f32 v[108:109], v[118:119], v[108:109], v[204:205] op_sel:[1,0,0] op_sel_hi:[1,1,0] neg_lo:[0,0,1] neg_hi:[0,0,1]
	v_and_b32_e32 v203, 0xffff0000, v110
	v_lshlrev_b32_e32 v110, 16, v111
	v_and_b32_e32 v111, 0xffff0000, v111
	v_pk_fma_f32 v[108:109], v[174:175], v[108:109], v[178:179]
	v_pk_fma_f32 v[200:201], v[118:119], v[200:201], v[204:205] op_sel:[1,0,0] op_sel_hi:[1,1,0] neg_lo:[0,0,1] neg_hi:[0,0,1]
	v_pk_fma_f32 v[94:95], v[94:95], v[182:183], v[108:109]
	v_pk_fma_f32 v[108:109], v[118:119], v[110:111], v[204:205] op_sel:[1,0,0] op_sel_hi:[1,1,0] neg_lo:[0,0,1] neg_hi:[0,0,1]
	v_pk_fma_f32 v[110:111], v[118:119], v[202:203], v[204:205] op_sel:[1,0,0] op_sel_hi:[1,1,0] neg_lo:[0,0,1] neg_hi:[0,0,1]
	v_pk_fma_f32 v[200:201], v[176:177], v[200:201], v[180:181]
	v_pk_fma_f32 v[110:111], v[164:165], v[110:111], v[172:173]
	v_pk_fma_f32 v[92:93], v[92:93], v[184:185], v[200:201]
	v_pk_fma_f32 v[108:109], v[162:163], v[108:109], v[166:167]
	v_pk_fma_f32 v[88:89], v[88:89], v[170:171], v[110:111]
	v_pk_fma_f32 v[108:109], v[90:91], v[168:169], v[108:109]
	v_cvt_pk_bf16_f32 v90, v92, v93
	v_cvt_pk_bf16_f32 v92, v88, v89
	v_add_co_u32_e32 v88, vcc, s62, v120
	v_cvt_pk_bf16_f32 v91, v94, v95
	v_cvt_pk_bf16_f32 v93, v108, v109
	v_addc_co_u32_e32 v89, vcc, 0, v121, vcc
	global_store_dwordx4 v[88:89], v[90:93], off
	s_waitcnt vmcnt(6)
	v_lshlrev_b32_e32 v94, 16, v116
	v_lshlrev_b32_e32 v92, 16, v115
	v_and_b32_e32 v93, 0xffff0000, v115
	s_waitcnt vmcnt(5)
	v_pk_mul_f32 v[110:111], v[126:127], v[126:127] op_sel:[0,1] op_sel_hi:[1,0]
	v_lshlrev_b32_e32 v90, 16, v114
	v_and_b32_e32 v91, 0xffff0000, v114
	v_pk_fma_f32 v[92:93], v[126:127], v[92:93], v[110:111] op_sel:[1,0,0] op_sel_hi:[1,1,0] neg_lo:[0,0,1] neg_hi:[0,0,1]
	v_and_b32_e32 v95, 0xffff0000, v116
	v_pk_fma_f32 v[90:91], v[126:127], v[90:91], v[110:111] op_sel:[1,0,0] op_sel_hi:[1,1,0] neg_lo:[0,0,1] neg_hi:[0,0,1]
	v_pk_fma_f32 v[92:93], v[174:175], v[92:93], v[178:179]
	v_lshlrev_b32_e32 v108, 16, v117
	v_and_b32_e32 v109, 0xffff0000, v117
	v_pk_fma_f32 v[90:91], v[176:177], v[90:91], v[180:181]
	v_pk_fma_f32 v[86:87], v[86:87], v[182:183], v[92:93]
	v_pk_fma_f32 v[92:93], v[126:127], v[94:95], v[110:111] op_sel:[1,0,0] op_sel_hi:[1,1,0] neg_lo:[0,0,1] neg_hi:[0,0,1]
	v_pk_fma_f32 v[84:85], v[84:85], v[184:185], v[90:91]
	v_pk_fma_f32 v[90:91], v[126:127], v[108:109], v[110:111] op_sel:[1,0,0] op_sel_hi:[1,1,0] neg_lo:[0,0,1] neg_hi:[0,0,1]
	v_pk_fma_f32 v[92:93], v[164:165], v[92:93], v[172:173]
	v_pk_fma_f32 v[90:91], v[162:163], v[90:91], v[166:167]
	v_pk_fma_f32 v[80:81], v[80:81], v[170:171], v[92:93]
	v_pk_fma_f32 v[90:91], v[82:83], v[168:169], v[90:91]
	v_cvt_pk_bf16_f32 v82, v84, v85
	v_cvt_pk_bf16_f32 v84, v80, v81
	v_add_co_u32_e32 v80, vcc, s63, v120
	v_cvt_pk_bf16_f32 v83, v86, v87
	v_cvt_pk_bf16_f32 v85, v90, v91
	v_addc_co_u32_e32 v81, vcc, 0, v121, vcc
	global_store_dwordx4 v[80:81], v[82:85], off
	s_waitcnt vmcnt(4)
; __device__ __forceinline__ u32x4 pack8f(f32x4 lo, f32x4 hi) { u32x4 w; w.x = cvtpk(lo[0], lo[1]); w.y = cvtpk(lo[2], lo[3]); w.z = cvtpk(hi[0], hi[1]); w.w = cvtpk(hi[2], hi[3]); return w; }
;     __device__ __forceinline__ void operator()(const Acc& acc, const Unit& u, int wr, int wc, int fr, int fq) const {
;     ...
;         for (int bj = 0; bj < 2; ++bj) {
;             f32x4 gm[2], G[2], Bc[2];
; #pragma unroll
;             for (int n = 0; n < 2; ++n) { const int c = col0 + bj * 128 + n * 4; gm[n] = *(const f32x4*)(gate + (size_t)b * NADA + c) + 1.0f; G[n] = *(const f32x4*)(lg + c) * ALPHA; Bc[n] = *(const f32x4*)(lb + c) * ALPHA; }
; #pragma unroll
;             for (int hf = 0; hf < 2; ++hf) {
;                 u32x4 yv[4]; f32x2 st[4];
; #pragma unroll
;                 for (int m = 0; m < 4; ++m) { const int row = rowb + hf * 128 + m * 16; yv[m] = *(const u32x4*)(y1 + yb + (size_t)(hf * 128 + m * 16) * 256 + bj * 128); st[m] = *(const f32x2*)(stats + (size_t)row * 2); }
; #pragma unroll
;                 for (int m = 0; m < 4; ++m) { const int row = rowb + hf * 128 + m * 16;
;                     f32x4 lo, hi; unpack8(yv[m], lo, hi); const float r = st[m][1], mr = st[m][0] * r;
;                     lo = (lo * r - mr) * G[0] + Bc[0] + gm[0] * acc[hf][bj][m][0]; hi = (hi * r - mr) * G[1] + Bc[1] + gm[1] * acc[hf][bj][m][1];
;                     *(u32x4*)(y2 + yb + (size_t)(hf * 128 + m * 16) * 256 + bj * 128) = pack8f(lo, hi); }
	v_pk_mul_f32 v[92:93], v[196:197], v[196:197] op_sel:[0,1] op_sel_hi:[1,0]
	v_lshlrev_b32_e32 v86, 16, v124
	v_lshlrev_b32_e32 v84, 16, v123
	v_and_b32_e32 v85, 0xffff0000, v123
	v_lshlrev_b32_e32 v82, 16, v122
	v_and_b32_e32 v83, 0xffff0000, v122
	v_pk_fma_f32 v[84:85], v[196:197], v[84:85], v[92:93] op_sel:[1,0,0] op_sel_hi:[1,1,0] neg_lo:[0,0,1] neg_hi:[0,0,1]
	v_and_b32_e32 v87, 0xffff0000, v124
	v_pk_fma_f32 v[82:83], v[196:197], v[82:83], v[92:93] op_sel:[1,0,0] op_sel_hi:[1,1,0] neg_lo:[0,0,1] neg_hi:[0,0,1]
	v_pk_fma_f32 v[84:85], v[174:175], v[84:85], v[178:179]
	v_lshlrev_b32_e32 v90, 16, v125
	v_and_b32_e32 v91, 0xffff0000, v125
	v_pk_fma_f32 v[82:83], v[176:177], v[82:83], v[180:181]
	v_pk_fma_f32 v[78:79], v[78:79], v[182:183], v[84:85]
	v_pk_fma_f32 v[84:85], v[196:197], v[86:87], v[92:93] op_sel:[1,0,0] op_sel_hi:[1,1,0] neg_lo:[0,0,1] neg_hi:[0,0,1]
	v_pk_fma_f32 v[76:77], v[76:77], v[184:185], v[82:83]
	v_pk_fma_f32 v[82:83], v[196:197], v[90:91], v[92:93] op_sel:[1,0,0] op_sel_hi:[1,1,0] neg_lo:[0,0,1] neg_hi:[0,0,1]
	v_pk_fma_f32 v[84:85], v[164:165], v[84:85], v[172:173]
	v_pk_fma_f32 v[82:83], v[162:163], v[82:83], v[166:167]
	v_pk_fma_f32 v[72:73], v[72:73], v[170:171], v[84:85]
	v_pk_fma_f32 v[82:83], v[74:75], v[168:169], v[82:83]
	v_cvt_pk_bf16_f32 v74, v76, v77
	v_cvt_pk_bf16_f32 v76, v72, v73
	v_add_co_u32_e32 v72, vcc, s64, v120
	v_cvt_pk_bf16_f32 v75, v78, v79
	v_cvt_pk_bf16_f32 v77, v82, v83
	v_addc_co_u32_e32 v73, vcc, 0, v121, vcc
	global_store_dwordx4 v[72:73], v[74:77], off
	s_waitcnt vmcnt(3)
	v_pk_mul_f32 v[84:85], v[198:199], v[198:199] op_sel:[0,1] op_sel_hi:[1,0]
	v_lshlrev_b32_e32 v78, 16, v194
	v_lshlrev_b32_e32 v76, 16, v193
	v_and_b32_e32 v77, 0xffff0000, v193
	v_lshlrev_b32_e32 v74, 16, v192
	v_and_b32_e32 v75, 0xffff0000, v192
	v_pk_fma_f32 v[76:77], v[198:199], v[76:77], v[84:85] op_sel:[1,0,0] op_sel_hi:[1,1,0] neg_lo:[0,0,1] neg_hi:[0,0,1]
	v_and_b32_e32 v79, 0xffff0000, v194
	v_pk_fma_f32 v[74:75], v[198:199], v[74:75], v[84:85] op_sel:[1,0,0] op_sel_hi:[1,1,0] neg_lo:[0,0,1] neg_hi:[0,0,1]
	v_pk_fma_f32 v[76:77], v[174:175], v[76:77], v[178:179]
	v_lshlrev_b32_e32 v82, 16, v195
	v_and_b32_e32 v83, 0xffff0000, v195
	v_pk_fma_f32 v[74:75], v[176:177], v[74:75], v[180:181]
	v_pk_fma_f32 v[70:71], v[70:71], v[182:183], v[76:77]
	v_pk_fma_f32 v[76:77], v[198:199], v[78:79], v[84:85] op_sel:[1,0,0] op_sel_hi:[1,1,0] neg_lo:[0,0,1] neg_hi:[0,0,1]
	v_pk_fma_f32 v[68:69], v[68:69], v[184:185], v[74:75]
	v_pk_fma_f32 v[74:75], v[198:199], v[82:83], v[84:85] op_sel:[1,0,0] op_sel_hi:[1,1,0] neg_lo:[0,0,1] neg_hi:[0,0,1]
	v_pk_fma_f32 v[76:77], v[164:165], v[76:77], v[172:173]
	v_pk_fma_f32 v[74:75], v[162:163], v[74:75], v[166:167]
	v_pk_fma_f32 v[64:65], v[64:65], v[170:171], v[76:77]
	v_pk_fma_f32 v[74:75], v[66:67], v[168:169], v[74:75]
	v_cvt_pk_bf16_f32 v66, v68, v69
	v_cvt_pk_bf16_f32 v68, v64, v65
	v_add_co_u32_e32 v64, vcc, s65, v120
	v_cvt_pk_bf16_f32 v67, v70, v71
	v_cvt_pk_bf16_f32 v69, v74, v75
	v_addc_co_u32_e32 v65, vcc, 0, v121, vcc
	global_store_dwordx4 v[64:65], v[66:69], off
	global_load_dwordx4 v[66:69], v[146:147], off offset:512
	global_load_dwordx4 v[82:85], v[142:143], off offset:512
	global_load_dwordx4 v[108:111], v[144:145], off offset:512
	global_load_dwordx4 v[114:117], v[146:147], off offset:528
	global_load_dwordx4 v[122:125], v[142:143], off offset:528
	s_nop 0
	global_load_dwordx4 v[142:145], v[144:145], off offset:528
	s_nop 0
	global_load_dwordx4 v[146:149], v[148:149], off offset:256
	s_nop 0
	global_load_dwordx2 v[118:119], v[140:141], off
	global_load_dwordx4 v[162:165], v[150:151], off offset:256
	global_load_dwordx2 v[126:127], v[152:153], off
	s_nop 0
	global_load_dwordx4 v[150:153], v[158:159], off offset:256
	s_nop 0
	global_load_dwordx2 v[158:159], v[160:161], off
	s_and_b64 vcc, exec, s[2:3]
	s_waitcnt vmcnt(11)
	v_pk_add_f32 v[74:75], v[68:69], 1.0 op_sel_hi:[1,0]
	v_pk_add_f32 v[76:77], v[66:67], 1.0 op_sel_hi:[1,0]
	s_waitcnt vmcnt(9)
	v_pk_mul_f32 v[92:93], v[110:111], s[28:29] op_sel_hi:[1,0]
	v_pk_mul_f32 v[94:95], v[108:109], s[28:29] op_sel_hi:[1,0]
	s_waitcnt vmcnt(8)
	v_pk_add_f32 v[68:69], v[114:115], 1.0 op_sel_hi:[1,0]
	global_load_dwordx4 v[108:111], v[156:157], off offset:256
	global_load_dwordx2 v[114:115], v[154:155], off
	v_pk_mul_f32 v[90:91], v[82:83], s[28:29] op_sel_hi:[1,0]
	v_pk_add_f32 v[66:67], v[116:117], 1.0 op_sel_hi:[1,0]
	s_waitcnt vmcnt(8)
	v_pk_mul_f32 v[82:83], v[144:145], s[28:29] op_sel_hi:[1,0]
	s_waitcnt vmcnt(7)
	v_lshlrev_b32_e32 v116, 16, v146
	v_and_b32_e32 v117, 0xffff0000, v146
	s_waitcnt vmcnt(6)
	v_pk_mul_f32 v[144:145], v[118:119], v[118:119] op_sel:[0,1] op_sel_hi:[1,0]
	v_pk_mul_f32 v[86:87], v[84:85], s[28:29] op_sel_hi:[1,0]
	v_pk_fma_f32 v[116:117], v[118:119], v[116:117], v[144:145] op_sel:[1,0,0] op_sel_hi:[1,1,0] neg_lo:[0,0,1] neg_hi:[0,0,1]
	v_pk_mul_f32 v[70:71], v[124:125], s[28:29] op_sel_hi:[1,0]
	v_pk_mul_f32 v[78:79], v[122:123], s[28:29] op_sel_hi:[1,0]
	v_pk_mul_f32 v[84:85], v[142:143], s[28:29] op_sel_hi:[1,0]
	v_lshlrev_b32_e32 v122, 16, v147
	v_and_b32_e32 v123, 0xffff0000, v147
	v_lshlrev_b32_e32 v124, 16, v148
	v_and_b32_e32 v125, 0xffff0000, v148
	v_lshlrev_b32_e32 v142, 16, v149
	v_and_b32_e32 v143, 0xffff0000, v149
	v_pk_fma_f32 v[116:117], v[90:91], v[116:117], v[94:95]
	v_pk_fma_f32 v[122:123], v[118:119], v[122:123], v[144:145] op_sel:[1,0,0] op_sel_hi:[1,1,0] neg_lo:[0,0,1] neg_hi:[0,0,1]
	v_pk_fma_f32 v[60:61], v[60:61], v[76:77], v[116:117]
	v_pk_fma_f32 v[116:117], v[118:119], v[124:125], v[144:145] op_sel:[1,0,0] op_sel_hi:[1,1,0] neg_lo:[0,0,1] neg_hi:[0,0,1]
	v_pk_fma_f32 v[118:119], v[118:119], v[142:143], v[144:145] op_sel:[1,0,0] op_sel_hi:[1,1,0] neg_lo:[0,0,1] neg_hi:[0,0,1]
	v_pk_fma_f32 v[122:123], v[86:87], v[122:123], v[92:93]
	v_pk_fma_f32 v[118:119], v[70:71], v[118:119], v[82:83]
	v_pk_fma_f32 v[116:117], v[78:79], v[116:117], v[84:85]
	v_pk_fma_f32 v[62:63], v[62:63], v[74:75], v[122:123]
	v_pk_fma_f32 v[118:119], v[58:59], v[66:67], v[118:119]
	v_pk_fma_f32 v[58:59], v[56:57], v[68:69], v[116:117]
	v_cvt_pk_bf16_f32 v56, v60, v61
	v_cvt_pk_bf16_f32 v57, v62, v63
	v_cvt_pk_bf16_f32 v58, v58, v59
	v_cvt_pk_bf16_f32 v59, v118, v119
	global_store_dwordx4 v[120:121], v[56:59], off offset:256
	s_waitcnt vmcnt(5)
; __device__ __forceinline__ u32x4 pack8f(f32x4 lo, f32x4 hi) { u32x4 w; w.x = cvtpk(lo[0], lo[1]); w.y = cvtpk(lo[2], lo[3]); w.z = cvtpk(hi[0], hi[1]); w.w = cvtpk(hi[2], hi[3]); return w; }
;     __device__ __forceinline__ void operator()(const Acc& acc, const Unit& u, int wr, int wc, int fr, int fq) const {
;     ...
;         for (int bj = 0; bj < 2; ++bj) {
;             f32x4 gm[2], G[2], Bc[2];
; #pragma unroll
;             for (int n = 0; n < 2; ++n) { const int c = col0 + bj * 128 + n * 4; gm[n] = *(const f32x4*)(gate + (size_t)b * NADA + c) + 1.0f; G[n] = *(const f32x4*)(lg + c) * ALPHA; Bc[n] = *(const f32x4*)(lb + c) * ALPHA; }
; #pragma unroll
;             for (int hf = 0; hf < 2; ++hf) {
;                 u32x4 yv[4]; f32x2 st[4];
; #pragma unroll
;                 for (int m = 0; m < 4; ++m) { const int row = rowb + hf * 128 + m * 16; yv[m] = *(const u32x4*)(y1 + yb + (size_t)(hf * 128 + m * 16) * 256 + bj * 128); st[m] = *(const f32x2*)(stats + (size_t)row * 2); }
; #pragma unroll
;                 for (int m = 0; m < 4; ++m) { const int row = rowb + hf * 128 + m * 16;
;                     f32x4 lo, hi; unpack8(yv[m], lo, hi); const float r = st[m][1], mr = st[m][0] * r;
;                     lo = (lo * r - mr) * G[0] + Bc[0] + gm[0] * acc[hf][bj][m][0]; hi = (hi * r - mr) * G[1] + Bc[1] + gm[1] * acc[hf][bj][m][1];
;                     *(u32x4*)(y2 + yb + (size_t)(hf * 128 + m * 16) * 256 + bj * 128) = pack8f(lo, hi); }
	v_pk_mul_f32 v[116:117], v[126:127], v[126:127] op_sel:[0,1] op_sel_hi:[1,0]
	v_lshlrev_b32_e32 v60, 16, v164
	v_lshlrev_b32_e32 v56, 16, v162
	v_and_b32_e32 v57, 0xffff0000, v162
	v_lshlrev_b32_e32 v58, 16, v163
	v_and_b32_e32 v59, 0xffff0000, v163
	v_pk_fma_f32 v[58:59], v[126:127], v[58:59], v[116:117] op_sel:[1,0,0] op_sel_hi:[1,1,0] neg_lo:[0,0,1] neg_hi:[0,0,1]
	v_pk_fma_f32 v[56:57], v[126:127], v[56:57], v[116:117] op_sel:[1,0,0] op_sel_hi:[1,1,0] neg_lo:[0,0,1] neg_hi:[0,0,1]
	v_and_b32_e32 v61, 0xffff0000, v164
	v_lshlrev_b32_e32 v62, 16, v165
	v_and_b32_e32 v63, 0xffff0000, v165
	v_pk_fma_f32 v[56:57], v[90:91], v[56:57], v[94:95]
	v_pk_fma_f32 v[58:59], v[86:87], v[58:59], v[92:93]
	v_pk_fma_f32 v[52:53], v[52:53], v[76:77], v[56:57]
	v_pk_fma_f32 v[54:55], v[54:55], v[74:75], v[58:59]
	v_pk_fma_f32 v[56:57], v[126:127], v[62:63], v[116:117] op_sel:[1,0,0] op_sel_hi:[1,1,0] neg_lo:[0,0,1] neg_hi:[0,0,1]
	v_pk_fma_f32 v[58:59], v[126:127], v[60:61], v[116:117] op_sel:[1,0,0] op_sel_hi:[1,1,0] neg_lo:[0,0,1] neg_hi:[0,0,1]
	v_pk_fma_f32 v[56:57], v[70:71], v[56:57], v[82:83]
	v_pk_fma_f32 v[58:59], v[78:79], v[58:59], v[84:85]
	v_pk_fma_f32 v[56:57], v[50:51], v[66:67], v[56:57]
	v_pk_fma_f32 v[50:51], v[48:49], v[68:69], v[58:59]
	v_cvt_pk_bf16_f32 v48, v52, v53
	v_cvt_pk_bf16_f32 v49, v54, v55
	v_cvt_pk_bf16_f32 v50, v50, v51
	v_cvt_pk_bf16_f32 v51, v56, v57
	global_store_dwordx4 v[112:113], v[48:51], off offset:256
	s_waitcnt vmcnt(4)
	v_pk_mul_f32 v[56:57], v[158:159], v[158:159] op_sel:[0,1] op_sel_hi:[1,0]
	v_lshlrev_b32_e32 v52, 16, v152
	v_lshlrev_b32_e32 v48, 16, v150
	v_and_b32_e32 v49, 0xffff0000, v150
	v_lshlrev_b32_e32 v50, 16, v151
	v_and_b32_e32 v51, 0xffff0000, v151
	v_pk_fma_f32 v[50:51], v[158:159], v[50:51], v[56:57] op_sel:[1,0,0] op_sel_hi:[1,1,0] neg_lo:[0,0,1] neg_hi:[0,0,1]
	v_pk_fma_f32 v[48:49], v[158:159], v[48:49], v[56:57] op_sel:[1,0,0] op_sel_hi:[1,1,0] neg_lo:[0,0,1] neg_hi:[0,0,1]
	v_and_b32_e32 v53, 0xffff0000, v152
	v_lshlrev_b32_e32 v54, 16, v153
	v_and_b32_e32 v55, 0xffff0000, v153
	v_pk_fma_f32 v[48:49], v[90:91], v[48:49], v[94:95]
	v_pk_fma_f32 v[50:51], v[86:87], v[50:51], v[92:93]
	v_pk_fma_f32 v[44:45], v[44:45], v[76:77], v[48:49]
	v_pk_fma_f32 v[46:47], v[46:47], v[74:75], v[50:51]
	v_pk_fma_f32 v[48:49], v[158:159], v[54:55], v[56:57] op_sel:[1,0,0] op_sel_hi:[1,1,0] neg_lo:[0,0,1] neg_hi:[0,0,1]
	v_pk_fma_f32 v[50:51], v[158:159], v[52:53], v[56:57] op_sel:[1,0,0] op_sel_hi:[1,1,0] neg_lo:[0,0,1] neg_hi:[0,0,1]
	v_pk_fma_f32 v[48:49], v[70:71], v[48:49], v[82:83]
	v_pk_fma_f32 v[50:51], v[78:79], v[50:51], v[84:85]
	v_pk_fma_f32 v[48:49], v[42:43], v[66:67], v[48:49]
	v_pk_fma_f32 v[42:43], v[40:41], v[68:69], v[50:51]
	v_cvt_pk_bf16_f32 v40, v44, v45
	v_cvt_pk_bf16_f32 v41, v46, v47
	v_cvt_pk_bf16_f32 v42, v42, v43
	v_cvt_pk_bf16_f32 v43, v48, v49
	global_store_dwordx4 v[104:105], v[40:43], off offset:256
	s_waitcnt vmcnt(3)
	v_pk_mul_f32 v[48:49], v[114:115], v[114:115] op_sel:[0,1] op_sel_hi:[1,0]
	v_lshlrev_b32_e32 v44, 16, v110
	v_lshlrev_b32_e32 v40, 16, v108
	v_and_b32_e32 v41, 0xffff0000, v108
	v_lshlrev_b32_e32 v42, 16, v109
	v_and_b32_e32 v43, 0xffff0000, v109
	v_pk_fma_f32 v[42:43], v[114:115], v[42:43], v[48:49] op_sel:[1,0,0] op_sel_hi:[1,1,0] neg_lo:[0,0,1] neg_hi:[0,0,1]
	v_pk_fma_f32 v[40:41], v[114:115], v[40:41], v[48:49] op_sel:[1,0,0] op_sel_hi:[1,1,0] neg_lo:[0,0,1] neg_hi:[0,0,1]
	v_and_b32_e32 v45, 0xffff0000, v110
	v_lshlrev_b32_e32 v46, 16, v111
	v_and_b32_e32 v47, 0xffff0000, v111
	v_pk_fma_f32 v[40:41], v[90:91], v[40:41], v[94:95]
	v_pk_fma_f32 v[42:43], v[86:87], v[42:43], v[92:93]
	v_pk_fma_f32 v[36:37], v[36:37], v[76:77], v[40:41]
	v_pk_fma_f32 v[38:39], v[38:39], v[74:75], v[42:43]
	v_pk_fma_f32 v[40:41], v[114:115], v[46:47], v[48:49] op_sel:[1,0,0] op_sel_hi:[1,1,0] neg_lo:[0,0,1] neg_hi:[0,0,1]
	v_pk_fma_f32 v[42:43], v[114:115], v[44:45], v[48:49] op_sel:[1,0,0] op_sel_hi:[1,1,0] neg_lo:[0,0,1] neg_hi:[0,0,1]
	v_pk_fma_f32 v[40:41], v[70:71], v[40:41], v[82:83]
	v_pk_fma_f32 v[42:43], v[78:79], v[42:43], v[84:85]
	v_pk_fma_f32 v[40:41], v[34:35], v[66:67], v[40:41]
	v_pk_fma_f32 v[34:35], v[32:33], v[68:69], v[42:43]
	v_cvt_pk_bf16_f32 v32, v36, v37
	v_cvt_pk_bf16_f32 v33, v38, v39
	v_cvt_pk_bf16_f32 v34, v34, v35
	v_cvt_pk_bf16_f32 v35, v40, v41
	global_store_dwordx4 v[96:97], v[32:35], off offset:256
	global_load_dwordx4 v[32:35], v[98:99], off offset:256
	global_load_dwordx2 v[48:49], v[140:141], off offset:1024
	global_load_dwordx4 v[36:39], v[100:101], off offset:256
	global_load_dwordx2 v[50:51], v[140:141], off offset:1152
	global_load_dwordx4 v[40:43], v[102:103], off offset:256
	global_load_dwordx2 v[52:53], v[140:141], off offset:1280
	global_load_dwordx4 v[44:47], v[106:107], off offset:256
	global_load_dwordx2 v[54:55], v[140:141], off offset:1408
	s_waitcnt vmcnt(7)
	v_lshlrev_b32_e32 v56, 16, v32
	v_and_b32_e32 v57, 0xffff0000, v32
	v_lshlrev_b32_e32 v32, 16, v33
	v_and_b32_e32 v33, 0xffff0000, v33
	s_waitcnt vmcnt(6)
; #define PG8_WAIT_V(n) asm volatile("s_waitcnt vmcnt(" #n ")" ::: "memory")
; #define PG8_BAR __builtin_amdgcn_s_barrier()
; __device__ __forceinline__ u32x4 pack8f(f32x4 lo, f32x4 hi) { u32x4 w; w.x = cvtpk(lo[0], lo[1]); w.y = cvtpk(lo[2], lo[3]); w.z = cvtpk(hi[0], hi[1]); w.w = cvtpk(hi[2], hi[3]); return w; }
;     ...
;         if (!has_next) break;
; #pragma unroll
;         for (int a = 0; a < 2; ++a)
; #pragma unroll
;             for (int b = 0; b < 2; ++b)
; #pragma unroll
;                 for (int m = 0; m < 4; ++m)
; #pragma unroll
;                     for (int n = 0; n < 2; ++n) acc[a][b][m][n] = (f32x4){0.f, 0.f, 0.f, 0.f};
;         cur = nxt; cA = nA; cB = nB; ++ui;
;         if constexpr (ALIGN) { if (wr == 1) PG8_BAR; }
;     }
;     PG8_WAIT_V(0);
;     if constexpr (!ALIGN) { if (wr == 0) PG8_BAR; }
;     PG8_BAR;
;     __device__ __forceinline__ void operator()(const Acc& acc, const Unit& u, int wr, int wc, int fr, int fq) const {
;     ...
;             for (int hf = 0; hf < 2; ++hf) {
;                 u32x4 yv[4]; f32x2 st[4];
; #pragma unroll
;                 for (int m = 0; m < 4; ++m) { const int row = rowb + hf * 128 + m * 16; yv[m] = *(const u32x4*)(y1 + yb + (size_t)(hf * 128 + m * 16) * 256 + bj * 128); st[m] = *(const f32x2*)(stats + (size_t)row * 2); }
; #pragma unroll
;                 for (int m = 0; m < 4; ++m) { const int row = rowb + hf * 128 + m * 16;
;                     f32x4 lo, hi; unpack8(yv[m], lo, hi); const float r = st[m][1], mr = st[m][0] * r;
;                     lo = (lo * r - mr) * G[0] + Bc[0] + gm[0] * acc[hf][bj][m][0]; hi = (hi * r - mr) * G[1] + Bc[1] + gm[1] * acc[hf][bj][m][1];
;                     *(u32x4*)(y2 + yb + (size_t)(hf * 128 + m * 16) * 256 + bj * 128) = pack8f(lo, hi); }
	v_pk_mul_f32 v[60:61], v[48:49], v[48:49] op_sel:[0,1] op_sel_hi:[1,0]
	v_lshlrev_b32_e32 v58, 16, v34
	v_pk_fma_f32 v[32:33], v[48:49], v[32:33], v[60:61] op_sel:[1,0,0] op_sel_hi:[1,1,0] neg_lo:[0,0,1] neg_hi:[0,0,1]
	v_and_b32_e32 v59, 0xffff0000, v34
	v_lshlrev_b32_e32 v34, 16, v35
	v_and_b32_e32 v35, 0xffff0000, v35
	v_pk_fma_f32 v[32:33], v[86:87], v[32:33], v[92:93]
	v_pk_fma_f32 v[56:57], v[48:49], v[56:57], v[60:61] op_sel:[1,0,0] op_sel_hi:[1,1,0] neg_lo:[0,0,1] neg_hi:[0,0,1]
	v_pk_fma_f32 v[30:31], v[30:31], v[74:75], v[32:33]
	v_pk_fma_f32 v[32:33], v[48:49], v[34:35], v[60:61] op_sel:[1,0,0] op_sel_hi:[1,1,0] neg_lo:[0,0,1] neg_hi:[0,0,1]
	v_pk_fma_f32 v[34:35], v[48:49], v[58:59], v[60:61] op_sel:[1,0,0] op_sel_hi:[1,1,0] neg_lo:[0,0,1] neg_hi:[0,0,1]
	v_pk_fma_f32 v[56:57], v[90:91], v[56:57], v[94:95]
	v_pk_fma_f32 v[34:35], v[78:79], v[34:35], v[84:85]
	v_pk_fma_f32 v[32:33], v[70:71], v[32:33], v[82:83]
	v_pk_fma_f32 v[28:29], v[28:29], v[76:77], v[56:57]
	v_pk_fma_f32 v[32:33], v[26:27], v[66:67], v[32:33]
	v_pk_fma_f32 v[26:27], v[24:25], v[68:69], v[34:35]
	v_cvt_pk_bf16_f32 v24, v28, v29
	v_cvt_pk_bf16_f32 v25, v30, v31
	v_cvt_pk_bf16_f32 v26, v26, v27
	v_cvt_pk_bf16_f32 v27, v32, v33
	global_store_dwordx4 v[88:89], v[24:27], off offset:256
	s_waitcnt vmcnt(5)
	v_pk_mul_f32 v[32:33], v[50:51], v[50:51] op_sel:[0,1] op_sel_hi:[1,0]
	v_lshlrev_b32_e32 v28, 16, v38
	v_lshlrev_b32_e32 v24, 16, v36
	v_and_b32_e32 v25, 0xffff0000, v36
	v_lshlrev_b32_e32 v26, 16, v37
	v_and_b32_e32 v27, 0xffff0000, v37
	v_pk_fma_f32 v[26:27], v[50:51], v[26:27], v[32:33] op_sel:[1,0,0] op_sel_hi:[1,1,0] neg_lo:[0,0,1] neg_hi:[0,0,1]
	v_pk_fma_f32 v[24:25], v[50:51], v[24:25], v[32:33] op_sel:[1,0,0] op_sel_hi:[1,1,0] neg_lo:[0,0,1] neg_hi:[0,0,1]
	v_and_b32_e32 v29, 0xffff0000, v38
	v_lshlrev_b32_e32 v30, 16, v39
	v_and_b32_e32 v31, 0xffff0000, v39
	v_pk_fma_f32 v[24:25], v[90:91], v[24:25], v[94:95]
	v_pk_fma_f32 v[26:27], v[86:87], v[26:27], v[92:93]
	v_pk_fma_f32 v[20:21], v[20:21], v[76:77], v[24:25]
	v_pk_fma_f32 v[22:23], v[22:23], v[74:75], v[26:27]
	v_pk_fma_f32 v[24:25], v[50:51], v[30:31], v[32:33] op_sel:[1,0,0] op_sel_hi:[1,1,0] neg_lo:[0,0,1] neg_hi:[0,0,1]
	v_pk_fma_f32 v[26:27], v[50:51], v[28:29], v[32:33] op_sel:[1,0,0] op_sel_hi:[1,1,0] neg_lo:[0,0,1] neg_hi:[0,0,1]
	v_pk_fma_f32 v[24:25], v[70:71], v[24:25], v[82:83]
	v_pk_fma_f32 v[26:27], v[78:79], v[26:27], v[84:85]
	v_pk_fma_f32 v[24:25], v[18:19], v[66:67], v[24:25]
	v_pk_fma_f32 v[18:19], v[16:17], v[68:69], v[26:27]
	v_cvt_pk_bf16_f32 v16, v20, v21
	v_cvt_pk_bf16_f32 v17, v22, v23
	v_cvt_pk_bf16_f32 v18, v18, v19
	v_cvt_pk_bf16_f32 v19, v24, v25
	global_store_dwordx4 v[80:81], v[16:19], off offset:256
	s_waitcnt vmcnt(4)
	v_pk_mul_f32 v[24:25], v[52:53], v[52:53] op_sel:[0,1] op_sel_hi:[1,0]
	v_lshlrev_b32_e32 v20, 16, v42
	v_lshlrev_b32_e32 v16, 16, v40
	v_and_b32_e32 v17, 0xffff0000, v40
	v_lshlrev_b32_e32 v18, 16, v41
	v_and_b32_e32 v19, 0xffff0000, v41
	v_pk_fma_f32 v[18:19], v[52:53], v[18:19], v[24:25] op_sel:[1,0,0] op_sel_hi:[1,1,0] neg_lo:[0,0,1] neg_hi:[0,0,1]
	v_pk_fma_f32 v[16:17], v[52:53], v[16:17], v[24:25] op_sel:[1,0,0] op_sel_hi:[1,1,0] neg_lo:[0,0,1] neg_hi:[0,0,1]
	v_and_b32_e32 v21, 0xffff0000, v42
	v_lshlrev_b32_e32 v22, 16, v43
	v_and_b32_e32 v23, 0xffff0000, v43
	v_pk_fma_f32 v[16:17], v[90:91], v[16:17], v[94:95]
	v_pk_fma_f32 v[18:19], v[86:87], v[18:19], v[92:93]
	v_pk_fma_f32 v[12:13], v[12:13], v[76:77], v[16:17]
	v_pk_fma_f32 v[14:15], v[14:15], v[74:75], v[18:19]
	v_pk_fma_f32 v[16:17], v[52:53], v[22:23], v[24:25] op_sel:[1,0,0] op_sel_hi:[1,1,0] neg_lo:[0,0,1] neg_hi:[0,0,1]
	v_pk_fma_f32 v[18:19], v[52:53], v[20:21], v[24:25] op_sel:[1,0,0] op_sel_hi:[1,1,0] neg_lo:[0,0,1] neg_hi:[0,0,1]
	v_pk_fma_f32 v[16:17], v[70:71], v[16:17], v[82:83]
	v_pk_fma_f32 v[18:19], v[78:79], v[18:19], v[84:85]
	v_pk_fma_f32 v[16:17], v[10:11], v[66:67], v[16:17]
	v_pk_fma_f32 v[10:11], v[8:9], v[68:69], v[18:19]
	v_cvt_pk_bf16_f32 v8, v12, v13
	v_cvt_pk_bf16_f32 v9, v14, v15
	v_cvt_pk_bf16_f32 v10, v10, v11
	v_cvt_pk_bf16_f32 v11, v16, v17
	global_store_dwordx4 v[72:73], v[8:11], off offset:256
	s_waitcnt vmcnt(3)
	v_pk_mul_f32 v[16:17], v[54:55], v[54:55] op_sel:[0,1] op_sel_hi:[1,0]
	v_lshlrev_b32_e32 v12, 16, v46
	v_lshlrev_b32_e32 v8, 16, v44
	v_and_b32_e32 v9, 0xffff0000, v44
	v_lshlrev_b32_e32 v10, 16, v45
	v_and_b32_e32 v11, 0xffff0000, v45
	v_pk_fma_f32 v[10:11], v[54:55], v[10:11], v[16:17] op_sel:[1,0,0] op_sel_hi:[1,1,0] neg_lo:[0,0,1] neg_hi:[0,0,1]
	v_pk_fma_f32 v[8:9], v[54:55], v[8:9], v[16:17] op_sel:[1,0,0] op_sel_hi:[1,1,0] neg_lo:[0,0,1] neg_hi:[0,0,1]
	v_and_b32_e32 v13, 0xffff0000, v46
	v_lshlrev_b32_e32 v14, 16, v47
	v_and_b32_e32 v15, 0xffff0000, v47
	v_pk_fma_f32 v[8:9], v[90:91], v[8:9], v[94:95]
	v_pk_fma_f32 v[10:11], v[86:87], v[10:11], v[92:93]
	v_pk_fma_f32 v[4:5], v[4:5], v[76:77], v[8:9]
	v_pk_fma_f32 v[6:7], v[6:7], v[74:75], v[10:11]
	v_pk_fma_f32 v[8:9], v[54:55], v[14:15], v[16:17] op_sel:[1,0,0] op_sel_hi:[1,1,0] neg_lo:[0,0,1] neg_hi:[0,0,1]
	v_pk_fma_f32 v[10:11], v[54:55], v[12:13], v[16:17] op_sel:[1,0,0] op_sel_hi:[1,1,0] neg_lo:[0,0,1] neg_hi:[0,0,1]
	v_pk_fma_f32 v[8:9], v[70:71], v[8:9], v[82:83]
	v_pk_fma_f32 v[10:11], v[78:79], v[10:11], v[84:85]
	v_pk_fma_f32 v[8:9], v[2:3], v[66:67], v[8:9]
	v_pk_fma_f32 v[2:3], v[0:1], v[68:69], v[10:11]
	v_cvt_pk_bf16_f32 v0, v4, v5
	v_cvt_pk_bf16_f32 v1, v6, v7
	v_cvt_pk_bf16_f32 v2, v2, v3
	v_cvt_pk_bf16_f32 v3, v8, v9
	global_store_dwordx4 v[64:65], v[0:3], off offset:256
	s_cbranch_vccz .LBB0_1274
	s_waitcnt vmcnt(0)
	s_cmpk_gt_u32 s29, 0xff
	s_cbranch_scc1 .LBB0_1285
	s_barrier
